# same as previous plus one wait state between each m0 write and the LDS-DMA that follows it (4 sites)
# speedup vs baseline: 1.0025x; 1.0025x over previous
; #define PG8_STAGE(bufoff, gbase, voff) do { _Pragma("unroll") for (int _i = 0; _i < 2; ++_i) \
;         __builtin_amdgcn_global_load_lds((const unsigned*)((const char*)(gbase) + (voff)[_i]), (PG8_LAS unsigned*)(lds + (bufoff) + ldsw + _i * 8192), 16, 0, 0); } while (0)
; #define PG8_LDA(dst, b, h) do { _Pragma("unroll") for (int m = 0; m < 4; ++m) _Pragma("unroll") for (int k = 0; k < 2; ++k) dst[m][k] = *(const PG8_LAS bf16x8*)(lds + PG8_SA(b, h) + aoff + m * 2048 + k * 1024); } while (0)
; #define PG8_LDB(dst, b, h) do { _Pragma("unroll") for (int n = 0; n < 2; ++n) _Pragma("unroll") for (int k = 0; k < 2; ++k) dst[n][k] = *(const PG8_LAS bf16x8*)(lds + PG8_SB(b, h) + boff + n * 2048 + k * 1024); } while (0)
; #define PG8_MMA(ai, bj, At, Bt) do { __builtin_amdgcn_s_setprio(1); _Pragma("unroll") for (int m = 0; m < 4; ++m) _Pragma("unroll") for (int n = 0; n < 2; ++n) _Pragma("unroll") for (int k = 0; k < 2; ++k) \
;         acc[ai][bj][m][n] = __builtin_amdgcn_mfma_f32_16x16x32_bf16(Bt[n][k], At[m][k], acc[ai][bj][m][n], 0, 0, 0); __builtin_amdgcn_s_setprio(0); } while (0)
; template <class Epi, class Sched, bool ALIGN_EPI = false, bool SP2 = false>
; __device__ __forceinline__ void gemm_phase(PG8_LAS unsigned char* lds, const Gemm g, const Sched& S, const Epi& E) {
;     ...
;             if constexpr (SP2) {
;             PG8_LDB(B0, 0, 0); PG8_LDB(B1, 0, 1); PG8_SCHED; PG8_LDA(At, 0, 0); PG8_STAGE(PG8_SA(1, 1), a1 + hstepA, voffA);
;             PG8_WAIT_V(8); PG8_WAIT_L(0); PG8_BAR; PG8_MMA(0, 0, At, B0); PG8_MMA(0, 1, At, B1); PG8_BAR; PG8_SCHED;
;             PG8_LDA(At, 0, 1); PG8_STAGE(PG8_SB(0, 0), b2, voffB); PG8_STAGE(PG8_SB(0, 1), b2 + hstepB, voffB); PG8_STAGE(PG8_SA(0, 0), a2, voffA);
;             PG8_WAIT_V(8); PG8_WAIT_L(0); PG8_BAR; PG8_MMA(1, 0, At, B0); PG8_MMA(1, 1, At, B1); PG8_BAR; PG8_SCHED;
;             PG8_LDB(B0, 1, 0); PG8_LDB(B1, 1, 1); PG8_SCHED; PG8_LDA(At, 1, 0); PG8_STAGE(PG8_SA(0, 1), a2 + hstepA, voffA);
;             PG8_WAIT_V(8); PG8_WAIT_L(0); PG8_BAR; PG8_MMA(0, 0, At, B0); PG8_MMA(0, 1, At, B1); PG8_BAR; PG8_SCHED;
;             PG8_LDA(At, 1, 1); PG8_STAGE(PG8_SB(1, 0), b3, voffB); PG8_STAGE(PG8_SB(1, 1), b3 + hstepB, voffB); PG8_STAGE(PG8_SA(1, 0), a3, voffA);
;             PG8_WAIT_V(8); PG8_WAIT_L(0); PG8_BAR; PG8_MMA(1, 0, At, B0); PG8_MMA(1, 1, At, B1); PG8_BAR; PG8_SCHED;
.LBB0_187:
	ds_read_b128 v[128:131], v173
	ds_read_b128 v[132:135], v173 offset:1024
	ds_read_b128 v[152:155], v173 offset:2048
	ds_read_b128 v[156:159], v173 offset:3072
	ds_read_b128 v[160:163], v174
	ds_read_b128 v[164:167], v174 offset:1024
	ds_read_b128 v[180:183], v174 offset:2048
	ds_read_b128 v[184:187], v174 offset:3072
	s_add_u32 s16, s12, 0xfff80080
	s_addc_u32 s17, s13, -1
	s_cmp_eq_u32 s61, 28
	s_cselect_b32 s19, s1, s17
	s_cselect_b32 s18, s26, s16
	s_cselect_b32 s17, s15, s60
	s_cselect_b32 s16, s36, s37
	v_lshl_add_u64 v[168:169], s[12:13], 0, v[144:145]
	s_add_i32 m0, s77, 0xc000
	ds_read_b128 v[188:191], v175
	ds_read_b128 v[192:195], v175 offset:1024
	ds_read_b128 v[196:199], v175 offset:2048
	ds_read_b128 v[200:203], v175 offset:3072
	ds_read_b128 v[204:207], v175 offset:4096
	ds_read_b128 v[208:211], v175 offset:5120
	ds_read_b128 v[212:215], v175 offset:6144
	ds_read_b128 v[216:219], v175 offset:7168
	s_add_u32 s98, s12, 0xfff80000
	s_addc_u32 s99, s13, -1
	s_mov_b32 m0, s7
	s_nop 0
	global_load_lds_dwordx4 v136, s[98:99]
	s_mov_b32 m0, s46
	s_nop 0
	global_load_lds_dwordx4 v140, s[98:99]
	s_add_i32 m0, s77, 0xc000
	s_nop 0
	global_load_lds_dwordx4 v[168:169], off
	v_lshl_add_u64 v[168:169], s[12:13], 0, v[146:147]
	s_add_i32 m0, s77, 0xe000
	s_nop 0
	global_load_lds_dwordx4 v[168:169], off
	s_waitcnt vmcnt(8)
	s_waitcnt lgkmcnt(0)
	s_barrier
	s_setprio 1
	s_waitcnt lgkmcnt(0)
	v_mfma_f32_16x16x32_bf16 v[124:127], v[128:131], v[188:191], v[124:127]
	v_mfma_f32_16x16x32_bf16 v[120:123], v[152:155], v[188:191], v[120:123]
	v_mfma_f32_16x16x32_bf16 v[108:111], v[128:131], v[196:199], v[108:111]
	v_mfma_f32_16x16x32_bf16 v[104:107], v[152:155], v[196:199], v[104:107]
	v_mfma_f32_16x16x32_bf16 v[92:95], v[128:131], v[204:207], v[92:95]
	v_mfma_f32_16x16x32_bf16 v[88:91], v[152:155], v[204:207], v[88:91]
	v_mfma_f32_16x16x32_bf16 v[76:79], v[128:131], v[212:215], v[76:79]
	v_mfma_f32_16x16x32_bf16 v[72:75], v[152:155], v[212:215], v[72:75]
	v_mfma_f32_16x16x32_bf16 v[124:127], v[132:135], v[192:195], v[124:127]
	v_mfma_f32_16x16x32_bf16 v[120:123], v[156:159], v[192:195], v[120:123]
	v_mfma_f32_16x16x32_bf16 v[108:111], v[132:135], v[200:203], v[108:111]
	v_mfma_f32_16x16x32_bf16 v[104:107], v[156:159], v[200:203], v[104:107]
	v_mfma_f32_16x16x32_bf16 v[92:95], v[132:135], v[208:211], v[92:95]
	v_mfma_f32_16x16x32_bf16 v[88:91], v[156:159], v[208:211], v[88:91]
	v_mfma_f32_16x16x32_bf16 v[76:79], v[132:135], v[216:219], v[76:79]
	v_mfma_f32_16x16x32_bf16 v[72:75], v[156:159], v[216:219], v[72:75]
	s_setprio 0
	s_setprio 1
	v_mfma_f32_16x16x32_bf16 v[116:119], v[160:163], v[188:191], v[116:119]
	v_mfma_f32_16x16x32_bf16 v[112:115], v[180:183], v[188:191], v[112:115]
	v_mfma_f32_16x16x32_bf16 v[100:103], v[160:163], v[196:199], v[100:103]
	v_mfma_f32_16x16x32_bf16 v[96:99], v[180:183], v[196:199], v[96:99]
	v_mfma_f32_16x16x32_bf16 v[84:87], v[160:163], v[204:207], v[84:87]
	v_mfma_f32_16x16x32_bf16 v[80:83], v[180:183], v[204:207], v[80:83]
	v_mfma_f32_16x16x32_bf16 v[68:71], v[160:163], v[212:215], v[68:71]
	v_mfma_f32_16x16x32_bf16 v[64:67], v[180:183], v[212:215], v[64:67]
	v_mfma_f32_16x16x32_bf16 v[116:119], v[164:167], v[192:195], v[116:119]
	v_mfma_f32_16x16x32_bf16 v[112:115], v[184:187], v[192:195], v[112:115]
	v_mfma_f32_16x16x32_bf16 v[100:103], v[164:167], v[200:203], v[100:103]
	v_mfma_f32_16x16x32_bf16 v[96:99], v[184:187], v[200:203], v[96:99]
	v_mfma_f32_16x16x32_bf16 v[84:87], v[164:167], v[208:211], v[84:87]
	v_mfma_f32_16x16x32_bf16 v[80:83], v[184:187], v[208:211], v[80:83]
	v_mfma_f32_16x16x32_bf16 v[68:71], v[164:167], v[216:219], v[68:71]
	v_mfma_f32_16x16x32_bf16 v[64:67], v[184:187], v[216:219], v[64:67]
	s_setprio 0
	s_barrier
	s_add_i32 s69, s47, s33
	v_lshl_add_u64 v[168:169], s[16:17], 0, v[138:139]
	s_mov_b32 m0, s69
	ds_read_b128 v[188:191], v175 offset:16384
	ds_read_b128 v[192:195], v175 offset:17408
	ds_read_b128 v[196:199], v175 offset:18432
	ds_read_b128 v[200:203], v175 offset:19456
	ds_read_b128 v[204:207], v175 offset:20480
	ds_read_b128 v[208:211], v175 offset:21504
	ds_read_b128 v[212:215], v175 offset:22528
	ds_read_b128 v[216:219], v175 offset:23552
	global_load_lds_dwordx4 v[168:169], off
	s_add_i32 m0, s69, 0x2000
	s_add_u32 s70, s16, 0x80000
	v_lshl_add_u64 v[220:221], s[16:17], 0, v[142:143]
	s_addc_u32 s71, s17, 0
	s_add_i32 s69, s56, s33
	global_load_lds_dwordx4 v[220:221], off
	v_lshl_add_u64 v[222:223], s[70:71], 0, v[138:139]
	s_mov_b32 m0, s69
	s_nop 0
	global_load_lds_dwordx4 v[222:223], off
	v_lshl_add_u64 v[222:223], s[70:71], 0, v[142:143]
	s_add_i32 m0, s69, 0x2000
	s_nop 0
	global_load_lds_dwordx4 v[222:223], off
	s_waitcnt vmcnt(6)
	s_waitcnt lgkmcnt(0)
	s_barrier
; #define PG8_STAGE(bufoff, gbase, voff) do { _Pragma("unroll") for (int _i = 0; _i < 2; ++_i) \
;         __builtin_amdgcn_global_load_lds((const unsigned*)((const char*)(gbase) + (voff)[_i]), (PG8_LAS unsigned*)(lds + (bufoff) + ldsw + _i * 8192), 16, 0, 0); } while (0)
; #define PG8_LDA(dst, b, h) do { _Pragma("unroll") for (int m = 0; m < 4; ++m) _Pragma("unroll") for (int k = 0; k < 2; ++k) dst[m][k] = *(const PG8_LAS bf16x8*)(lds + PG8_SA(b, h) + aoff + m * 2048 + k * 1024); } while (0)
; #define PG8_LDB(dst, b, h) do { _Pragma("unroll") for (int n = 0; n < 2; ++n) _Pragma("unroll") for (int k = 0; k < 2; ++k) dst[n][k] = *(const PG8_LAS bf16x8*)(lds + PG8_SB(b, h) + boff + n * 2048 + k * 1024); } while (0)
; #define PG8_MMA(ai, bj, At, Bt) do { __builtin_amdgcn_s_setprio(1); _Pragma("unroll") for (int m = 0; m < 4; ++m) _Pragma("unroll") for (int n = 0; n < 2; ++n) _Pragma("unroll") for (int k = 0; k < 2; ++k) \
;         acc[ai][bj][m][n] = __builtin_amdgcn_mfma_f32_16x16x32_bf16(Bt[n][k], At[m][k], acc[ai][bj][m][n], 0, 0, 0); __builtin_amdgcn_s_setprio(0); } while (0)
; template <class Epi, class Sched, bool ALIGN_EPI = false, bool SP2 = false>
; __device__ __forceinline__ void gemm_phase(PG8_LAS unsigned char* lds, const Gemm g, const Sched& S, const Epi& E) {
;     ...
;             if constexpr (SP2) {
;             PG8_LDB(B0, 0, 0); PG8_LDB(B1, 0, 1); PG8_SCHED; PG8_LDA(At, 0, 0); PG8_STAGE(PG8_SA(1, 1), a1 + hstepA, voffA);
;             PG8_WAIT_V(8); PG8_WAIT_L(0); PG8_BAR; PG8_MMA(0, 0, At, B0); PG8_MMA(0, 1, At, B1); PG8_BAR; PG8_SCHED;
;             PG8_LDA(At, 0, 1); PG8_STAGE(PG8_SB(0, 0), b2, voffB); PG8_STAGE(PG8_SB(0, 1), b2 + hstepB, voffB); PG8_STAGE(PG8_SA(0, 0), a2, voffA);
;             PG8_WAIT_V(8); PG8_WAIT_L(0); PG8_BAR; PG8_MMA(1, 0, At, B0); PG8_MMA(1, 1, At, B1); PG8_BAR; PG8_SCHED;
;             PG8_LDB(B0, 1, 0); PG8_LDB(B1, 1, 1); PG8_SCHED; PG8_LDA(At, 1, 0); PG8_STAGE(PG8_SA(0, 1), a2 + hstepA, voffA);
;             PG8_WAIT_V(8); PG8_WAIT_L(0); PG8_BAR; PG8_MMA(0, 0, At, B0); PG8_MMA(0, 1, At, B1); PG8_BAR; PG8_SCHED;
;             PG8_LDA(At, 1, 1); PG8_STAGE(PG8_SB(1, 0), b3, voffB); PG8_STAGE(PG8_SB(1, 1), b3 + hstepB, voffB); PG8_STAGE(PG8_SA(1, 0), a3, voffA);
;             PG8_WAIT_V(8); PG8_WAIT_L(0); PG8_BAR; PG8_MMA(1, 0, At, B0); PG8_MMA(1, 1, At, B1); PG8_BAR; PG8_SCHED;
	s_setprio 1
	s_waitcnt lgkmcnt(0)
	v_mfma_f32_16x16x32_bf16 v[60:63], v[128:131], v[188:191], v[60:63]
	v_mfma_f32_16x16x32_bf16 v[56:59], v[152:155], v[188:191], v[56:59]
	v_mfma_f32_16x16x32_bf16 v[44:47], v[128:131], v[196:199], v[44:47]
	v_mfma_f32_16x16x32_bf16 v[40:43], v[152:155], v[196:199], v[40:43]
	v_mfma_f32_16x16x32_bf16 v[28:31], v[128:131], v[204:207], v[28:31]
	v_mfma_f32_16x16x32_bf16 v[24:27], v[152:155], v[204:207], v[24:27]
	v_mfma_f32_16x16x32_bf16 v[12:15], v[128:131], v[212:215], v[12:15]
	v_mfma_f32_16x16x32_bf16 v[8:11], v[152:155], v[212:215], v[8:11]
	v_mfma_f32_16x16x32_bf16 v[60:63], v[132:135], v[192:195], v[60:63]
	v_mfma_f32_16x16x32_bf16 v[56:59], v[156:159], v[192:195], v[56:59]
	v_mfma_f32_16x16x32_bf16 v[44:47], v[132:135], v[200:203], v[44:47]
	v_mfma_f32_16x16x32_bf16 v[40:43], v[156:159], v[200:203], v[40:43]
	v_mfma_f32_16x16x32_bf16 v[28:31], v[132:135], v[208:211], v[28:31]
	v_mfma_f32_16x16x32_bf16 v[24:27], v[156:159], v[208:211], v[24:27]
	v_mfma_f32_16x16x32_bf16 v[12:15], v[132:135], v[216:219], v[12:15]
	v_mfma_f32_16x16x32_bf16 v[8:11], v[156:159], v[216:219], v[8:11]
	s_setprio 0
	s_setprio 1
	v_mfma_f32_16x16x32_bf16 v[52:55], v[160:163], v[188:191], v[52:55]
	v_mfma_f32_16x16x32_bf16 v[48:51], v[180:183], v[188:191], v[48:51]
	v_mfma_f32_16x16x32_bf16 v[36:39], v[160:163], v[196:199], v[36:39]
	v_mfma_f32_16x16x32_bf16 v[32:35], v[180:183], v[196:199], v[32:35]
	v_mfma_f32_16x16x32_bf16 v[20:23], v[160:163], v[204:207], v[20:23]
	v_mfma_f32_16x16x32_bf16 v[16:19], v[180:183], v[204:207], v[16:19]
	v_mfma_f32_16x16x32_bf16 v[4:7], v[160:163], v[212:215], v[4:7]
	v_mfma_f32_16x16x32_bf16 v[0:3], v[180:183], v[212:215], v[0:3]
	v_mfma_f32_16x16x32_bf16 v[52:55], v[164:167], v[192:195], v[52:55]
	v_mfma_f32_16x16x32_bf16 v[48:51], v[184:187], v[192:195], v[48:51]
	v_mfma_f32_16x16x32_bf16 v[36:39], v[164:167], v[200:203], v[36:39]
	v_mfma_f32_16x16x32_bf16 v[32:35], v[184:187], v[200:203], v[32:35]
	v_mfma_f32_16x16x32_bf16 v[20:23], v[164:167], v[208:211], v[20:23]
	v_mfma_f32_16x16x32_bf16 v[16:19], v[184:187], v[208:211], v[16:19]
	v_mfma_f32_16x16x32_bf16 v[4:7], v[164:167], v[216:219], v[4:7]
	v_mfma_f32_16x16x32_bf16 v[0:3], v[184:187], v[216:219], v[0:3]
	s_setprio 0
	s_barrier
	s_add_i32 s69, 0, 0x18000
	s_add_i32 s70, 0, 0x1c000
	v_add_u32_e32 v156, s69, v172
	v_add_u32_e32 v179, s70, v172
	ds_read_b128 v[128:131], v156
	ds_read_b128 v[132:135], v156 offset:1024
	ds_read_b128 v[152:155], v156 offset:2048
	ds_read_b128 v[156:159], v156 offset:3072
	ds_read_b128 v[160:163], v179
	ds_read_b128 v[164:167], v179 offset:1024
	ds_read_b128 v[180:183], v179 offset:2048
	ds_read_b128 v[184:187], v179 offset:3072
	s_mov_b64 s[100:101], s[18:19]
	s_add_u32 s18, s18, 0x80000
	s_addc_u32 s19, s19, 0
	s_mov_b32 m0, s23
	v_lshl_add_u64 v[226:227], s[18:19], 0, v[136:137]
	ds_read_b128 v[188:191], v175 offset:32768
	ds_read_b128 v[192:195], v175 offset:33792
	ds_read_b128 v[196:199], v175 offset:34816
	ds_read_b128 v[200:203], v175 offset:35840
	ds_read_b128 v[204:207], v175 offset:36864
	ds_read_b128 v[208:211], v175 offset:37888
	ds_read_b128 v[212:215], v175 offset:38912
	ds_read_b128 v[216:219], v175 offset:39936
	s_mov_b32 m0, s77
	s_nop 0
	global_load_lds_dwordx4 v136, s[100:101]
	s_mov_b32 m0, s22
	s_nop 0
	global_load_lds_dwordx4 v140, s[100:101]
	s_mov_b32 m0, s23
	s_nop 0
	global_load_lds_dwordx4 v[226:227], off
	v_lshl_add_u64 v[226:227], s[18:19], 0, v[140:141]
	s_mov_b32 m0, s4
	s_nop 0
	global_load_lds_dwordx4 v[226:227], off
	s_waitcnt vmcnt(8)
	s_waitcnt lgkmcnt(0)
	s_barrier
; #define PG8_STAGE(bufoff, gbase, voff) do { _Pragma("unroll") for (int _i = 0; _i < 2; ++_i) \
;         __builtin_amdgcn_global_load_lds((const unsigned*)((const char*)(gbase) + (voff)[_i]), (PG8_LAS unsigned*)(lds + (bufoff) + ldsw + _i * 8192), 16, 0, 0); } while (0)
; #define PG8_LDA(dst, b, h) do { _Pragma("unroll") for (int m = 0; m < 4; ++m) _Pragma("unroll") for (int k = 0; k < 2; ++k) dst[m][k] = *(const PG8_LAS bf16x8*)(lds + PG8_SA(b, h) + aoff + m * 2048 + k * 1024); } while (0)
; #define PG8_MMA(ai, bj, At, Bt) do { __builtin_amdgcn_s_setprio(1); _Pragma("unroll") for (int m = 0; m < 4; ++m) _Pragma("unroll") for (int n = 0; n < 2; ++n) _Pragma("unroll") for (int k = 0; k < 2; ++k) \
;         acc[ai][bj][m][n] = __builtin_amdgcn_mfma_f32_16x16x32_bf16(Bt[n][k], At[m][k], acc[ai][bj][m][n], 0, 0, 0); __builtin_amdgcn_s_setprio(0); } while (0)
; #define PG8_WAIT_V(n) asm volatile("s_waitcnt vmcnt(" #n ")" ::: "memory")
; #define PG8_WAIT_L(n) asm volatile("s_waitcnt lgkmcnt(" #n ")" ::: "memory")
; #define PG8_BAR __builtin_amdgcn_s_barrier()
; #define PG8_SCHED __builtin_amdgcn_sched_barrier(0)
; template <class Epi, class Sched, bool ALIGN_EPI = false, bool SP2 = false>
; __device__ __forceinline__ void gemm_phase(PG8_LAS unsigned char* lds, const Gemm g, const Sched& S, const Epi& E) {
;     ...
;             PG8_WAIT_V(8); PG8_WAIT_L(0); PG8_BAR; PG8_MMA(0, 0, At, B0); PG8_MMA(0, 1, At, B1); PG8_BAR; PG8_SCHED;
;             PG8_LDA(At, 1, 1); PG8_STAGE(PG8_SB(1, 0), b3, voffB); PG8_STAGE(PG8_SB(1, 1), b3 + hstepB, voffB); PG8_STAGE(PG8_SA(1, 0), a3, voffA);
;             PG8_WAIT_V(8); PG8_WAIT_L(0); PG8_BAR; PG8_MMA(1, 0, At, B0); PG8_MMA(1, 1, At, B1); PG8_BAR; PG8_SCHED;
;     ...
;         if constexpr (ALIGN_EPI) { if (wr == 0) PG8_BAR; }
	s_setprio 1
	s_waitcnt lgkmcnt(0)
	v_mfma_f32_16x16x32_bf16 v[124:127], v[128:131], v[188:191], v[124:127]
	v_mfma_f32_16x16x32_bf16 v[120:123], v[152:155], v[188:191], v[120:123]
	v_mfma_f32_16x16x32_bf16 v[108:111], v[128:131], v[196:199], v[108:111]
	v_mfma_f32_16x16x32_bf16 v[104:107], v[152:155], v[196:199], v[104:107]
	v_mfma_f32_16x16x32_bf16 v[92:95], v[128:131], v[204:207], v[92:95]
	v_mfma_f32_16x16x32_bf16 v[88:91], v[152:155], v[204:207], v[88:91]
	v_mfma_f32_16x16x32_bf16 v[76:79], v[128:131], v[212:215], v[76:79]
	v_mfma_f32_16x16x32_bf16 v[72:75], v[152:155], v[212:215], v[72:75]
	v_mfma_f32_16x16x32_bf16 v[124:127], v[132:135], v[192:195], v[124:127]
	v_mfma_f32_16x16x32_bf16 v[120:123], v[156:159], v[192:195], v[120:123]
	v_mfma_f32_16x16x32_bf16 v[108:111], v[132:135], v[200:203], v[108:111]
	v_mfma_f32_16x16x32_bf16 v[104:107], v[156:159], v[200:203], v[104:107]
	v_mfma_f32_16x16x32_bf16 v[92:95], v[132:135], v[208:211], v[92:95]
	v_mfma_f32_16x16x32_bf16 v[88:91], v[156:159], v[208:211], v[88:91]
	v_mfma_f32_16x16x32_bf16 v[76:79], v[132:135], v[216:219], v[76:79]
	v_mfma_f32_16x16x32_bf16 v[72:75], v[156:159], v[216:219], v[72:75]
	s_setprio 0
	s_setprio 1
	v_mfma_f32_16x16x32_bf16 v[116:119], v[160:163], v[188:191], v[116:119]
	v_mfma_f32_16x16x32_bf16 v[112:115], v[180:183], v[188:191], v[112:115]
	v_mfma_f32_16x16x32_bf16 v[100:103], v[160:163], v[196:199], v[100:103]
	v_mfma_f32_16x16x32_bf16 v[96:99], v[180:183], v[196:199], v[96:99]
	v_mfma_f32_16x16x32_bf16 v[84:87], v[160:163], v[204:207], v[84:87]
	v_mfma_f32_16x16x32_bf16 v[80:83], v[180:183], v[204:207], v[80:83]
	v_mfma_f32_16x16x32_bf16 v[68:71], v[160:163], v[212:215], v[68:71]
	v_mfma_f32_16x16x32_bf16 v[64:67], v[180:183], v[212:215], v[64:67]
	v_mfma_f32_16x16x32_bf16 v[116:119], v[164:167], v[192:195], v[116:119]
	v_mfma_f32_16x16x32_bf16 v[112:115], v[184:187], v[192:195], v[112:115]
	v_mfma_f32_16x16x32_bf16 v[100:103], v[164:167], v[200:203], v[100:103]
	v_mfma_f32_16x16x32_bf16 v[96:99], v[184:187], v[200:203], v[96:99]
	v_mfma_f32_16x16x32_bf16 v[84:87], v[164:167], v[208:211], v[84:87]
	v_mfma_f32_16x16x32_bf16 v[80:83], v[184:187], v[208:211], v[80:83]
	v_mfma_f32_16x16x32_bf16 v[68:71], v[164:167], v[216:219], v[68:71]
	v_mfma_f32_16x16x32_bf16 v[64:67], v[184:187], v[216:219], v[64:67]
	s_setprio 0
	s_barrier
	s_add_i32 s18, s69, s33
	v_lshl_add_u64 v[168:169], v[168:169], 0, s[30:31]
	s_mov_b32 m0, s18
	ds_read_b128 v[188:191], v175 offset:49152
	ds_read_b128 v[192:195], v175 offset:50176
	ds_read_b128 v[196:199], v175 offset:51200
	ds_read_b128 v[200:203], v175 offset:52224
	ds_read_b128 v[204:207], v175 offset:53248
	ds_read_b128 v[208:211], v175 offset:54272
	ds_read_b128 v[212:215], v175 offset:55296
	ds_read_b128 v[216:219], v175 offset:56320
	global_load_lds_dwordx4 v[168:169], off
	s_add_i32 m0, s18, 0x2000
	s_add_u32 s16, s16, 0x80080
	v_lshl_add_u64 v[168:169], v[220:221], 0, s[30:31]
	s_addc_u32 s17, s17, 0
	s_add_i32 s18, s70, s33
	global_load_lds_dwordx4 v[168:169], off
	v_lshl_add_u64 v[168:169], s[16:17], 0, v[138:139]
	s_mov_b32 m0, s18
	s_nop 0
	global_load_lds_dwordx4 v[168:169], off
	v_lshl_add_u64 v[168:169], s[16:17], 0, v[142:143]
	s_add_i32 m0, s18, 0x2000
	s_nop 0
	global_load_lds_dwordx4 v[168:169], off
	s_waitcnt vmcnt(6)
	s_waitcnt lgkmcnt(0)
	s_barrier
	s_setprio 1
	s_waitcnt lgkmcnt(0)
	v_mfma_f32_16x16x32_bf16 v[60:63], v[128:131], v[188:191], v[60:63]
	v_mfma_f32_16x16x32_bf16 v[56:59], v[152:155], v[188:191], v[56:59]
	v_mfma_f32_16x16x32_bf16 v[44:47], v[128:131], v[196:199], v[44:47]
	v_mfma_f32_16x16x32_bf16 v[40:43], v[152:155], v[196:199], v[40:43]
	v_mfma_f32_16x16x32_bf16 v[28:31], v[128:131], v[204:207], v[28:31]
	v_mfma_f32_16x16x32_bf16 v[24:27], v[152:155], v[204:207], v[24:27]
	v_mfma_f32_16x16x32_bf16 v[12:15], v[128:131], v[212:215], v[12:15]
	v_mfma_f32_16x16x32_bf16 v[8:11], v[152:155], v[212:215], v[8:11]
	v_mfma_f32_16x16x32_bf16 v[60:63], v[132:135], v[192:195], v[60:63]
	v_mfma_f32_16x16x32_bf16 v[56:59], v[156:159], v[192:195], v[56:59]
	v_mfma_f32_16x16x32_bf16 v[44:47], v[132:135], v[200:203], v[44:47]
	v_mfma_f32_16x16x32_bf16 v[40:43], v[156:159], v[200:203], v[40:43]
	v_mfma_f32_16x16x32_bf16 v[28:31], v[132:135], v[208:211], v[28:31]
	v_mfma_f32_16x16x32_bf16 v[24:27], v[156:159], v[208:211], v[24:27]
	v_mfma_f32_16x16x32_bf16 v[12:15], v[132:135], v[216:219], v[12:15]
	v_mfma_f32_16x16x32_bf16 v[8:11], v[156:159], v[216:219], v[8:11]
	s_setprio 0
	s_setprio 1
	v_mfma_f32_16x16x32_bf16 v[52:55], v[160:163], v[188:191], v[52:55]
	v_mfma_f32_16x16x32_bf16 v[48:51], v[180:183], v[188:191], v[48:51]
	v_mfma_f32_16x16x32_bf16 v[36:39], v[160:163], v[196:199], v[36:39]
	v_mfma_f32_16x16x32_bf16 v[32:35], v[180:183], v[196:199], v[32:35]
	v_mfma_f32_16x16x32_bf16 v[20:23], v[160:163], v[204:207], v[20:23]
	v_mfma_f32_16x16x32_bf16 v[16:19], v[180:183], v[204:207], v[16:19]
	v_mfma_f32_16x16x32_bf16 v[4:7], v[160:163], v[212:215], v[4:7]
	v_mfma_f32_16x16x32_bf16 v[0:3], v[180:183], v[212:215], v[0:3]
	v_mfma_f32_16x16x32_bf16 v[52:55], v[164:167], v[192:195], v[52:55]
	v_mfma_f32_16x16x32_bf16 v[48:51], v[184:187], v[192:195], v[48:51]
	v_mfma_f32_16x16x32_bf16 v[36:39], v[164:167], v[200:203], v[36:39]
	v_mfma_f32_16x16x32_bf16 v[32:35], v[184:187], v[200:203], v[32:35]
	v_mfma_f32_16x16x32_bf16 v[20:23], v[164:167], v[208:211], v[20:23]
	v_mfma_f32_16x16x32_bf16 v[16:19], v[184:187], v[208:211], v[16:19]
	v_mfma_f32_16x16x32_bf16 v[4:7], v[164:167], v[216:219], v[4:7]
	v_mfma_f32_16x16x32_bf16 v[0:3], v[184:187], v[216:219], v[0:3]
	s_setprio 0
	s_barrier
	s_add_i32 s61, s61, 2
	s_add_u32 s12, s12, 0x100
	s_addc_u32 s13, s13, 0
	s_add_u32 s37, s37, 0x100
	s_addc_u32 s60, s60, 0
	s_cmp_gt_u32 s61, 29
	s_cbranch_scc0 .LBB0_187
	s_and_b64 vcc, exec, s[96:97]
	s_cbranch_vccz .LBB0_190
	s_barrier

; #define PG8_STAGE(bufoff, gbase, voff) do { _Pragma("unroll") for (int _i = 0; _i < 2; ++_i) \
;         __builtin_amdgcn_global_load_lds((const unsigned*)((const char*)(gbase) + (voff)[_i]), (PG8_LAS unsigned*)(lds + (bufoff) + ldsw + _i * 8192), 16, 0, 0); } while (0)
; #define PG8_LDA(dst, b, h) do { _Pragma("unroll") for (int m = 0; m < 4; ++m) _Pragma("unroll") for (int k = 0; k < 2; ++k) dst[m][k] = *(const PG8_LAS bf16x8*)(lds + PG8_SA(b, h) + aoff + m * 2048 + k * 1024); } while (0)
; #define PG8_LDB(dst, b, h) do { _Pragma("unroll") for (int n = 0; n < 2; ++n) _Pragma("unroll") for (int k = 0; k < 2; ++k) dst[n][k] = *(const PG8_LAS bf16x8*)(lds + PG8_SB(b, h) + boff + n * 2048 + k * 1024); } while (0)
; #define PG8_WAIT_V(n) asm volatile("s_waitcnt vmcnt(" #n ")" ::: "memory")
; #define PG8_WAIT_L(n) asm volatile("s_waitcnt lgkmcnt(" #n ")" ::: "memory")
; #define PG8_BAR __builtin_amdgcn_s_barrier()
; #define PG8_SCHED __builtin_amdgcn_sched_barrier(0)
; template <class Epi, class Sched, bool ALIGN_EPI = false, bool SP2 = false>
; __device__ __forceinline__ void gemm_phase(PG8_LAS unsigned char* lds, const Gemm g, const Sched& S, const Epi& E) {
;     ...
;         const char* nA = has_next ? (const char*)g.A + (size_t)nxt.pm * tstepA : cA; const char* nB = has_next ? (const char*)g.Bt + (size_t)nxt.pn * tstepB : cB;
;         for (int t = 0; t < nt; t += 2) {
;             const bool last = (t == nt - 2);
;             if constexpr (Epi::HAS_MID) { if (t == E.mid_t) E.mid(acc, cur, wr, wc, fr, fq); }
;             const char* a1 = cA + (size_t)(t + 1) * kstep;
;             const char* a2 = last ? nA : cA + (size_t)(t + 2) * kstep; const char* b2 = last ? nB : cB + (size_t)(t + 2) * kstep;
;             const char* a3 = a2 + kstep; const char* b3 = b2 + kstep;
;             if (last && has_next) S.a_ready(nxt);
;             if constexpr (SP2) {
;             PG8_LDB(B0, 0, 0); PG8_LDB(B1, 0, 1); PG8_SCHED; PG8_LDA(At, 0, 0); PG8_STAGE(PG8_SA(1, 1), a1 + hstepA, voffA);
;             PG8_WAIT_V(8); PG8_WAIT_L(0); PG8_BAR; PG8_MMA(0, 0, At, B0); PG8_MMA(0, 1, At, B1); PG8_BAR; PG8_SCHED;
;             PG8_LDA(At, 0, 1); PG8_STAGE(PG8_SB(0, 0), b2, voffB); PG8_STAGE(PG8_SB(0, 1), b2 + hstepB, voffB); PG8_STAGE(PG8_SA(0, 0), a2, voffA);
;             PG8_WAIT_V(8); PG8_WAIT_L(0); PG8_BAR; PG8_MMA(1, 0, At, B0); PG8_MMA(1, 1, At, B1); PG8_BAR; PG8_SCHED;
.Lp7_full_loop:
.LBB0_1824:
	ds_read_b128 v[144:147], v151
	ds_read_b128 v[156:159], v151 offset:1024
	ds_read_b128 v[160:163], v151 offset:2048
	ds_read_b128 v[164:167], v151 offset:3072
	ds_read_b128 v[168:171], v152
	ds_read_b128 v[172:175], v152 offset:1024
	ds_read_b128 v[176:179], v152 offset:2048
	ds_read_b128 v[180:183], v152 offset:3072
	s_add_u32 s34, s30, 0xfff80080
	s_addc_u32 s35, s31, -1
	s_cmp_eq_u32 s62, 28
	s_cselect_b32 s39, s21, s35
	s_cselect_b32 s38, s25, s34
	s_cselect_b32 s35, s23, s61
	s_cselect_b32 s34, s59, s60
	v_lshl_add_u64 v[216:217], s[30:31], 0, v[136:137]
	s_add_i32 m0, s6, 0xc000
	ds_read_b128 v[184:187], v153
	ds_read_b128 v[188:191], v153 offset:1024
	ds_read_b128 v[192:195], v153 offset:2048
	ds_read_b128 v[196:199], v153 offset:3072
	ds_read_b128 v[200:203], v153 offset:4096
	ds_read_b128 v[204:207], v153 offset:5120
	ds_read_b128 v[208:211], v153 offset:6144
	ds_read_b128 v[212:215], v153 offset:7168
	s_add_u32 s98, s30, 0xfff80000
	s_addc_u32 s99, s31, -1
	s_mov_b32 m0, s46
	s_nop 0
	global_load_lds_dwordx4 v134, s[98:99]
	s_mov_b32 m0, s47
	s_nop 0
	global_load_lds_dwordx4 v130, s[98:99]
	s_add_i32 m0, s6, 0xc000
	s_nop 0
	global_load_lds_dwordx4 v[216:217], off
	v_lshl_add_u64 v[216:217], s[30:31], 0, v[138:139]
	s_add_i32 m0, s6, 0xe000
	s_nop 0
	global_load_lds_dwordx4 v[216:217], off
	s_waitcnt vmcnt(8)
	s_waitcnt lgkmcnt(0)
	s_barrier
	s_setprio 1
	s_waitcnt lgkmcnt(0)
	v_mfma_f32_16x16x32_bf16 v[124:127], v[144:147], v[184:187], v[124:127]
	v_mfma_f32_16x16x32_bf16 v[116:119], v[160:163], v[184:187], v[116:119]
	v_mfma_f32_16x16x32_bf16 v[108:111], v[144:147], v[192:195], v[108:111]
	v_mfma_f32_16x16x32_bf16 v[100:103], v[160:163], v[192:195], v[100:103]
	v_mfma_f32_16x16x32_bf16 v[92:95], v[144:147], v[200:203], v[92:95]
	v_mfma_f32_16x16x32_bf16 v[84:87], v[160:163], v[200:203], v[84:87]
	v_mfma_f32_16x16x32_bf16 v[76:79], v[144:147], v[208:211], v[76:79]
	v_mfma_f32_16x16x32_bf16 v[68:71], v[160:163], v[208:211], v[68:71]
	v_mfma_f32_16x16x32_bf16 v[124:127], v[156:159], v[188:191], v[124:127]
	v_mfma_f32_16x16x32_bf16 v[116:119], v[164:167], v[188:191], v[116:119]
	v_mfma_f32_16x16x32_bf16 v[108:111], v[156:159], v[196:199], v[108:111]
	v_mfma_f32_16x16x32_bf16 v[100:103], v[164:167], v[196:199], v[100:103]
	v_mfma_f32_16x16x32_bf16 v[92:95], v[156:159], v[204:207], v[92:95]
	v_mfma_f32_16x16x32_bf16 v[84:87], v[164:167], v[204:207], v[84:87]
	v_mfma_f32_16x16x32_bf16 v[76:79], v[156:159], v[212:215], v[76:79]
	v_mfma_f32_16x16x32_bf16 v[68:71], v[164:167], v[212:215], v[68:71]
	s_setprio 0
	s_setprio 1
	v_mfma_f32_16x16x32_bf16 v[120:123], v[168:171], v[184:187], v[120:123]
	v_mfma_f32_16x16x32_bf16 v[112:115], v[176:179], v[184:187], v[112:115]
	v_mfma_f32_16x16x32_bf16 v[104:107], v[168:171], v[192:195], v[104:107]
	v_mfma_f32_16x16x32_bf16 v[96:99], v[176:179], v[192:195], v[96:99]
	v_mfma_f32_16x16x32_bf16 v[88:91], v[168:171], v[200:203], v[88:91]
	v_mfma_f32_16x16x32_bf16 v[80:83], v[176:179], v[200:203], v[80:83]
	v_mfma_f32_16x16x32_bf16 v[72:75], v[168:171], v[208:211], v[72:75]
	v_mfma_f32_16x16x32_bf16 v[64:67], v[176:179], v[208:211], v[64:67]
	v_mfma_f32_16x16x32_bf16 v[120:123], v[172:175], v[188:191], v[120:123]
	v_mfma_f32_16x16x32_bf16 v[112:115], v[180:183], v[188:191], v[112:115]
	v_mfma_f32_16x16x32_bf16 v[104:107], v[172:175], v[196:199], v[104:107]
	v_mfma_f32_16x16x32_bf16 v[96:99], v[180:183], v[196:199], v[96:99]
	v_mfma_f32_16x16x32_bf16 v[88:91], v[172:175], v[204:207], v[88:91]
	v_mfma_f32_16x16x32_bf16 v[80:83], v[180:183], v[204:207], v[80:83]
	v_mfma_f32_16x16x32_bf16 v[72:75], v[172:175], v[212:215], v[72:75]
	v_mfma_f32_16x16x32_bf16 v[64:67], v[180:183], v[212:215], v[64:67]
	s_setprio 0
	s_barrier
	s_add_i32 s63, s53, s4
	v_lshl_add_u64 v[216:217], s[34:35], 0, v[132:133]
	s_mov_b32 m0, s63
	ds_read_b128 v[184:187], v153 offset:16384
	ds_read_b128 v[188:191], v153 offset:17408
	ds_read_b128 v[192:195], v153 offset:18432
	ds_read_b128 v[196:199], v153 offset:19456
	ds_read_b128 v[200:203], v153 offset:20480
	ds_read_b128 v[204:207], v153 offset:21504
	ds_read_b128 v[208:211], v153 offset:22528
	ds_read_b128 v[212:215], v153 offset:23552
	global_load_lds_dwordx4 v[216:217], off
	s_add_i32 m0, s63, 0x2000
	s_add_u32 s64, s34, 0x80000
	v_lshl_add_u64 v[218:219], s[34:35], 0, v[128:129]
	s_addc_u32 s65, s35, 0
	s_add_i32 s63, s54, s4
	global_load_lds_dwordx4 v[218:219], off
	v_lshl_add_u64 v[220:221], s[64:65], 0, v[132:133]
	s_mov_b32 m0, s63
	s_nop 0
	global_load_lds_dwordx4 v[220:221], off
	v_lshl_add_u64 v[220:221], s[64:65], 0, v[128:129]
	s_add_i32 m0, s63, 0x2000
	s_nop 0
	global_load_lds_dwordx4 v[220:221], off
	s_waitcnt vmcnt(6)
	s_waitcnt lgkmcnt(0)
	s_barrier
; #define PG8_STAGE(bufoff, gbase, voff) do { _Pragma("unroll") for (int _i = 0; _i < 2; ++_i) \
;         __builtin_amdgcn_global_load_lds((const unsigned*)((const char*)(gbase) + (voff)[_i]), (PG8_LAS unsigned*)(lds + (bufoff) + ldsw + _i * 8192), 16, 0, 0); } while (0)
; #define PG8_LDA(dst, b, h) do { _Pragma("unroll") for (int m = 0; m < 4; ++m) _Pragma("unroll") for (int k = 0; k < 2; ++k) dst[m][k] = *(const PG8_LAS bf16x8*)(lds + PG8_SA(b, h) + aoff + m * 2048 + k * 1024); } while (0)
; #define PG8_LDB(dst, b, h) do { _Pragma("unroll") for (int n = 0; n < 2; ++n) _Pragma("unroll") for (int k = 0; k < 2; ++k) dst[n][k] = *(const PG8_LAS bf16x8*)(lds + PG8_SB(b, h) + boff + n * 2048 + k * 1024); } while (0)
; #define PG8_MMA(ai, bj, At, Bt) do { __builtin_amdgcn_s_setprio(1); _Pragma("unroll") for (int m = 0; m < 4; ++m) _Pragma("unroll") for (int n = 0; n < 2; ++n) _Pragma("unroll") for (int k = 0; k < 2; ++k) \
;         acc[ai][bj][m][n] = __builtin_amdgcn_mfma_f32_16x16x32_bf16(Bt[n][k], At[m][k], acc[ai][bj][m][n], 0, 0, 0); __builtin_amdgcn_s_setprio(0); } while (0)
; #define PG8_WAIT_V(n) asm volatile("s_waitcnt vmcnt(" #n ")" ::: "memory")
; #define PG8_WAIT_L(n) asm volatile("s_waitcnt lgkmcnt(" #n ")" ::: "memory")
; #define PG8_BAR __builtin_amdgcn_s_barrier()
; #define PG8_SCHED __builtin_amdgcn_sched_barrier(0)
; template <class Epi, class Sched, bool ALIGN_EPI = false, bool SP2 = false>
; __device__ __forceinline__ void gemm_phase(PG8_LAS unsigned char* lds, const Gemm g, const Sched& S, const Epi& E) {
;     ...
;             PG8_WAIT_V(8); PG8_WAIT_L(0); PG8_BAR; PG8_MMA(1, 0, At, B0); PG8_MMA(1, 1, At, B1); PG8_BAR; PG8_SCHED;
;             PG8_LDB(B0, 1, 0); PG8_LDB(B1, 1, 1); PG8_SCHED; PG8_LDA(At, 1, 0); PG8_STAGE(PG8_SA(0, 1), a2 + hstepA, voffA);
;             PG8_WAIT_V(8); PG8_WAIT_L(0); PG8_BAR; PG8_MMA(0, 0, At, B0); PG8_MMA(0, 1, At, B1); PG8_BAR; PG8_SCHED;
	s_setprio 1
	s_waitcnt lgkmcnt(0)
	v_mfma_f32_16x16x32_bf16 v[60:63], v[144:147], v[184:187], v[60:63]
	v_mfma_f32_16x16x32_bf16 v[52:55], v[160:163], v[184:187], v[52:55]
	v_mfma_f32_16x16x32_bf16 v[44:47], v[144:147], v[192:195], v[44:47]
	v_mfma_f32_16x16x32_bf16 v[36:39], v[160:163], v[192:195], v[36:39]
	v_mfma_f32_16x16x32_bf16 v[28:31], v[144:147], v[200:203], v[28:31]
	v_mfma_f32_16x16x32_bf16 v[20:23], v[160:163], v[200:203], v[20:23]
	v_mfma_f32_16x16x32_bf16 v[12:15], v[144:147], v[208:211], v[12:15]
	v_mfma_f32_16x16x32_bf16 v[4:7], v[160:163], v[208:211], v[4:7]
	v_mfma_f32_16x16x32_bf16 v[60:63], v[156:159], v[188:191], v[60:63]
	v_mfma_f32_16x16x32_bf16 v[52:55], v[164:167], v[188:191], v[52:55]
	v_mfma_f32_16x16x32_bf16 v[44:47], v[156:159], v[196:199], v[44:47]
	v_mfma_f32_16x16x32_bf16 v[36:39], v[164:167], v[196:199], v[36:39]
	v_mfma_f32_16x16x32_bf16 v[28:31], v[156:159], v[204:207], v[28:31]
	v_mfma_f32_16x16x32_bf16 v[20:23], v[164:167], v[204:207], v[20:23]
	v_mfma_f32_16x16x32_bf16 v[12:15], v[156:159], v[212:215], v[12:15]
	v_mfma_f32_16x16x32_bf16 v[4:7], v[164:167], v[212:215], v[4:7]
	s_setprio 0
	s_setprio 1
	v_mfma_f32_16x16x32_bf16 v[56:59], v[168:171], v[184:187], v[56:59]
	v_mfma_f32_16x16x32_bf16 v[48:51], v[176:179], v[184:187], v[48:51]
	v_mfma_f32_16x16x32_bf16 v[40:43], v[168:171], v[192:195], v[40:43]
	v_mfma_f32_16x16x32_bf16 v[32:35], v[176:179], v[192:195], v[32:35]
	v_mfma_f32_16x16x32_bf16 v[24:27], v[168:171], v[200:203], v[24:27]
	v_mfma_f32_16x16x32_bf16 v[16:19], v[176:179], v[200:203], v[16:19]
	v_mfma_f32_16x16x32_bf16 v[8:11], v[168:171], v[208:211], v[8:11]
	v_mfma_f32_16x16x32_bf16 v[0:3], v[176:179], v[208:211], v[0:3]
	v_mfma_f32_16x16x32_bf16 v[56:59], v[172:175], v[188:191], v[56:59]
	v_mfma_f32_16x16x32_bf16 v[48:51], v[180:183], v[188:191], v[48:51]
	v_mfma_f32_16x16x32_bf16 v[40:43], v[172:175], v[196:199], v[40:43]
	v_mfma_f32_16x16x32_bf16 v[32:35], v[180:183], v[196:199], v[32:35]
	v_mfma_f32_16x16x32_bf16 v[24:27], v[172:175], v[204:207], v[24:27]
	v_mfma_f32_16x16x32_bf16 v[16:19], v[180:183], v[204:207], v[16:19]
	v_mfma_f32_16x16x32_bf16 v[8:11], v[172:175], v[212:215], v[8:11]
	v_mfma_f32_16x16x32_bf16 v[0:3], v[180:183], v[212:215], v[0:3]
	s_setprio 0
	s_barrier
	s_add_i32 s63, 0, 0x18000
	v_add_u32_e32 v155, s63, v150
	s_add_i32 s64, 0, 0x1c000
	ds_read_b128 v[144:147], v155
	ds_read_b128 v[156:159], v155 offset:1024
	ds_read_b128 v[160:163], v155 offset:2048
	ds_read_b128 v[164:167], v155 offset:3072
	v_add_u32_e32 v155, s64, v150
	ds_read_b128 v[168:171], v155
	ds_read_b128 v[172:175], v155 offset:1024
	ds_read_b128 v[176:179], v155 offset:2048
	ds_read_b128 v[180:183], v155 offset:3072
	s_mov_b64 s[100:101], s[38:39]
	s_add_u32 s38, s38, 0x80000
	s_addc_u32 s39, s39, 0
	s_mov_b32 m0, s41
	v_lshl_add_u64 v[224:225], s[38:39], 0, v[134:135]
	ds_read_b128 v[184:187], v153 offset:32768
	ds_read_b128 v[188:191], v153 offset:33792
	ds_read_b128 v[192:195], v153 offset:34816
	ds_read_b128 v[196:199], v153 offset:35840
	ds_read_b128 v[200:203], v153 offset:36864
	ds_read_b128 v[204:207], v153 offset:37888
	ds_read_b128 v[208:211], v153 offset:38912
	ds_read_b128 v[212:215], v153 offset:39936
	s_mov_b32 m0, s6
	s_nop 0
	global_load_lds_dwordx4 v134, s[100:101]
	s_mov_b32 m0, s7
	s_nop 0
	global_load_lds_dwordx4 v130, s[100:101]
	s_mov_b32 m0, s41
	s_nop 0
	global_load_lds_dwordx4 v[224:225], off
	v_lshl_add_u64 v[224:225], s[38:39], 0, v[130:131]
	s_mov_b32 m0, s42
	s_nop 0
	global_load_lds_dwordx4 v[224:225], off
	s_waitcnt vmcnt(8)
	s_waitcnt lgkmcnt(0)
	s_barrier
; #define PG8_STAGE(bufoff, gbase, voff) do { _Pragma("unroll") for (int _i = 0; _i < 2; ++_i) \
;         __builtin_amdgcn_global_load_lds((const unsigned*)((const char*)(gbase) + (voff)[_i]), (PG8_LAS unsigned*)(lds + (bufoff) + ldsw + _i * 8192), 16, 0, 0); } while (0)
; #define PG8_LDA(dst, b, h) do { _Pragma("unroll") for (int m = 0; m < 4; ++m) _Pragma("unroll") for (int k = 0; k < 2; ++k) dst[m][k] = *(const PG8_LAS bf16x8*)(lds + PG8_SA(b, h) + aoff + m * 2048 + k * 1024); } while (0)
; #define PG8_MMA(ai, bj, At, Bt) do { __builtin_amdgcn_s_setprio(1); _Pragma("unroll") for (int m = 0; m < 4; ++m) _Pragma("unroll") for (int n = 0; n < 2; ++n) _Pragma("unroll") for (int k = 0; k < 2; ++k) \
;         acc[ai][bj][m][n] = __builtin_amdgcn_mfma_f32_16x16x32_bf16(Bt[n][k], At[m][k], acc[ai][bj][m][n], 0, 0, 0); __builtin_amdgcn_s_setprio(0); } while (0)
; #define PG8_WAIT_V(n) asm volatile("s_waitcnt vmcnt(" #n ")" ::: "memory")
; #define PG8_WAIT_L(n) asm volatile("s_waitcnt lgkmcnt(" #n ")" ::: "memory")
; #define PG8_BAR __builtin_amdgcn_s_barrier()
; #define PG8_SCHED __builtin_amdgcn_sched_barrier(0)
; template <class Epi, class Sched, bool ALIGN_EPI = false, bool SP2 = false>
; __device__ __forceinline__ void gemm_phase(PG8_LAS unsigned char* lds, const Gemm g, const Sched& S, const Epi& E) {
;     ...
;             PG8_WAIT_V(8); PG8_WAIT_L(0); PG8_BAR; PG8_MMA(0, 0, At, B0); PG8_MMA(0, 1, At, B1); PG8_BAR; PG8_SCHED;
;             PG8_LDA(At, 1, 1); PG8_STAGE(PG8_SB(1, 0), b3, voffB); PG8_STAGE(PG8_SB(1, 1), b3 + hstepB, voffB); PG8_STAGE(PG8_SA(1, 0), a3, voffA);
;             PG8_WAIT_V(8); PG8_WAIT_L(0); PG8_BAR; PG8_MMA(1, 0, At, B0); PG8_MMA(1, 1, At, B1); PG8_BAR; PG8_SCHED;
	s_setprio 1
	s_waitcnt lgkmcnt(0)
	v_mfma_f32_16x16x32_bf16 v[124:127], v[144:147], v[184:187], v[124:127]
	v_mfma_f32_16x16x32_bf16 v[116:119], v[160:163], v[184:187], v[116:119]
	v_mfma_f32_16x16x32_bf16 v[108:111], v[144:147], v[192:195], v[108:111]
	v_mfma_f32_16x16x32_bf16 v[100:103], v[160:163], v[192:195], v[100:103]
	v_mfma_f32_16x16x32_bf16 v[92:95], v[144:147], v[200:203], v[92:95]
	v_mfma_f32_16x16x32_bf16 v[84:87], v[160:163], v[200:203], v[84:87]
	v_mfma_f32_16x16x32_bf16 v[76:79], v[144:147], v[208:211], v[76:79]
	v_mfma_f32_16x16x32_bf16 v[68:71], v[160:163], v[208:211], v[68:71]
	v_mfma_f32_16x16x32_bf16 v[124:127], v[156:159], v[188:191], v[124:127]
	v_mfma_f32_16x16x32_bf16 v[116:119], v[164:167], v[188:191], v[116:119]
	v_mfma_f32_16x16x32_bf16 v[108:111], v[156:159], v[196:199], v[108:111]
	v_mfma_f32_16x16x32_bf16 v[100:103], v[164:167], v[196:199], v[100:103]
	v_mfma_f32_16x16x32_bf16 v[92:95], v[156:159], v[204:207], v[92:95]
	v_mfma_f32_16x16x32_bf16 v[84:87], v[164:167], v[204:207], v[84:87]
	v_mfma_f32_16x16x32_bf16 v[76:79], v[156:159], v[212:215], v[76:79]
	v_mfma_f32_16x16x32_bf16 v[68:71], v[164:167], v[212:215], v[68:71]
	s_setprio 0
	s_setprio 1
	v_mfma_f32_16x16x32_bf16 v[120:123], v[168:171], v[184:187], v[120:123]
	v_mfma_f32_16x16x32_bf16 v[112:115], v[176:179], v[184:187], v[112:115]
	v_mfma_f32_16x16x32_bf16 v[104:107], v[168:171], v[192:195], v[104:107]
	v_mfma_f32_16x16x32_bf16 v[96:99], v[176:179], v[192:195], v[96:99]
	v_mfma_f32_16x16x32_bf16 v[88:91], v[168:171], v[200:203], v[88:91]
	v_mfma_f32_16x16x32_bf16 v[80:83], v[176:179], v[200:203], v[80:83]
	v_mfma_f32_16x16x32_bf16 v[72:75], v[168:171], v[208:211], v[72:75]
	v_mfma_f32_16x16x32_bf16 v[64:67], v[176:179], v[208:211], v[64:67]
	v_mfma_f32_16x16x32_bf16 v[120:123], v[172:175], v[188:191], v[120:123]
	v_mfma_f32_16x16x32_bf16 v[112:115], v[180:183], v[188:191], v[112:115]
	v_mfma_f32_16x16x32_bf16 v[104:107], v[172:175], v[196:199], v[104:107]
	v_mfma_f32_16x16x32_bf16 v[96:99], v[180:183], v[196:199], v[96:99]
	v_mfma_f32_16x16x32_bf16 v[88:91], v[172:175], v[204:207], v[88:91]
	v_mfma_f32_16x16x32_bf16 v[80:83], v[180:183], v[204:207], v[80:83]
	v_mfma_f32_16x16x32_bf16 v[72:75], v[172:175], v[212:215], v[72:75]
	v_mfma_f32_16x16x32_bf16 v[64:67], v[180:183], v[212:215], v[64:67]
	s_setprio 0
	s_barrier
	s_add_i32 s38, s63, s4
	v_lshl_add_u64 v[216:217], v[216:217], 0, s[16:17]
	s_mov_b32 m0, s38
	ds_read_b128 v[184:187], v153 offset:49152
	ds_read_b128 v[188:191], v153 offset:50176
	ds_read_b128 v[192:195], v153 offset:51200
	ds_read_b128 v[196:199], v153 offset:52224
	ds_read_b128 v[200:203], v153 offset:53248
	ds_read_b128 v[204:207], v153 offset:54272
	ds_read_b128 v[208:211], v153 offset:55296
	ds_read_b128 v[212:215], v153 offset:56320
	global_load_lds_dwordx4 v[216:217], off
	s_add_i32 m0, s38, 0x2000
	s_add_u32 s34, s34, 0x80080
	v_lshl_add_u64 v[216:217], v[218:219], 0, s[16:17]
	s_addc_u32 s35, s35, 0
	s_add_i32 s38, s64, s4
	global_load_lds_dwordx4 v[216:217], off
	v_lshl_add_u64 v[216:217], s[34:35], 0, v[132:133]
	s_mov_b32 m0, s38
	s_nop 0
	global_load_lds_dwordx4 v[216:217], off
	v_lshl_add_u64 v[216:217], s[34:35], 0, v[128:129]
	s_add_i32 m0, s38, 0x2000
	s_nop 0
	global_load_lds_dwordx4 v[216:217], off
	s_waitcnt vmcnt(6)
	s_waitcnt lgkmcnt(0)
	s_barrier
	s_setprio 1
	s_waitcnt lgkmcnt(0)
	v_mfma_f32_16x16x32_bf16 v[60:63], v[144:147], v[184:187], v[60:63]
	v_mfma_f32_16x16x32_bf16 v[52:55], v[160:163], v[184:187], v[52:55]
	v_mfma_f32_16x16x32_bf16 v[44:47], v[144:147], v[192:195], v[44:47]
	v_mfma_f32_16x16x32_bf16 v[36:39], v[160:163], v[192:195], v[36:39]
	v_mfma_f32_16x16x32_bf16 v[28:31], v[144:147], v[200:203], v[28:31]
	v_mfma_f32_16x16x32_bf16 v[20:23], v[160:163], v[200:203], v[20:23]
	v_mfma_f32_16x16x32_bf16 v[12:15], v[144:147], v[208:211], v[12:15]
	v_mfma_f32_16x16x32_bf16 v[4:7], v[160:163], v[208:211], v[4:7]
	v_mfma_f32_16x16x32_bf16 v[60:63], v[156:159], v[188:191], v[60:63]
	v_mfma_f32_16x16x32_bf16 v[52:55], v[164:167], v[188:191], v[52:55]
	v_mfma_f32_16x16x32_bf16 v[44:47], v[156:159], v[196:199], v[44:47]
	v_mfma_f32_16x16x32_bf16 v[36:39], v[164:167], v[196:199], v[36:39]
	v_mfma_f32_16x16x32_bf16 v[28:31], v[156:159], v[204:207], v[28:31]
	v_mfma_f32_16x16x32_bf16 v[20:23], v[164:167], v[204:207], v[20:23]
	v_mfma_f32_16x16x32_bf16 v[12:15], v[156:159], v[212:215], v[12:15]
	v_mfma_f32_16x16x32_bf16 v[4:7], v[164:167], v[212:215], v[4:7]
	s_setprio 0
	s_setprio 1
	v_mfma_f32_16x16x32_bf16 v[56:59], v[168:171], v[184:187], v[56:59]
	v_mfma_f32_16x16x32_bf16 v[48:51], v[176:179], v[184:187], v[48:51]
	v_mfma_f32_16x16x32_bf16 v[40:43], v[168:171], v[192:195], v[40:43]
	v_mfma_f32_16x16x32_bf16 v[32:35], v[176:179], v[192:195], v[32:35]
	v_mfma_f32_16x16x32_bf16 v[24:27], v[168:171], v[200:203], v[24:27]
	v_mfma_f32_16x16x32_bf16 v[16:19], v[176:179], v[200:203], v[16:19]
	v_mfma_f32_16x16x32_bf16 v[8:11], v[168:171], v[208:211], v[8:11]
	v_mfma_f32_16x16x32_bf16 v[0:3], v[176:179], v[208:211], v[0:3]
	v_mfma_f32_16x16x32_bf16 v[56:59], v[172:175], v[188:191], v[56:59]
	v_mfma_f32_16x16x32_bf16 v[48:51], v[180:183], v[188:191], v[48:51]
	v_mfma_f32_16x16x32_bf16 v[40:43], v[172:175], v[196:199], v[40:43]
	v_mfma_f32_16x16x32_bf16 v[32:35], v[180:183], v[196:199], v[32:35]
	v_mfma_f32_16x16x32_bf16 v[24:27], v[172:175], v[204:207], v[24:27]
	v_mfma_f32_16x16x32_bf16 v[16:19], v[180:183], v[204:207], v[16:19]
	v_mfma_f32_16x16x32_bf16 v[8:11], v[172:175], v[212:215], v[8:11]
	v_mfma_f32_16x16x32_bf16 v[0:3], v[180:183], v[212:215], v[0:3]
	s_setprio 0
	s_barrier
	s_add_i32 s62, s62, 2
	s_add_u32 s30, s30, 0x100
	s_addc_u32 s31, s31, 0
	s_add_u32 s60, s60, 0x100
	s_addc_u32 s61, s61, 0
	s_cmp_gt_u32 s62, 29
	s_cbranch_scc0 .LBB0_1824

; #define PG8_STAGE(bufoff, gbase, voff) do { _Pragma("unroll") for (int _i = 0; _i < 2; ++_i) \
;         __builtin_amdgcn_global_load_lds((const unsigned*)((const char*)(gbase) + (voff)[_i]), (PG8_LAS unsigned*)(lds + (bufoff) + ldsw + _i * 8192), 16, 0, 0); } while (0)
; #define PG8_LDA(dst, b, h) do { _Pragma("unroll") for (int m = 0; m < 4; ++m) _Pragma("unroll") for (int k = 0; k < 2; ++k) dst[m][k] = *(const PG8_LAS bf16x8*)(lds + PG8_SA(b, h) + aoff + m * 2048 + k * 1024); } while (0)
; #define PG8_LDB(dst, b, h) do { _Pragma("unroll") for (int n = 0; n < 2; ++n) _Pragma("unroll") for (int k = 0; k < 2; ++k) dst[n][k] = *(const PG8_LAS bf16x8*)(lds + PG8_SB(b, h) + boff + n * 2048 + k * 1024); } while (0)
; #define PG8_WAIT_V(n) asm volatile("s_waitcnt vmcnt(" #n ")" ::: "memory")
; #define PG8_WAIT_L(n) asm volatile("s_waitcnt lgkmcnt(" #n ")" ::: "memory")
; template <class Epi, class Sched, bool ALIGN_EPI = false, bool SP2 = false>
; __device__ __forceinline__ void gemm_phase(PG8_LAS unsigned char* lds, const Gemm g, const Sched& S, const Epi& E) {
;     ...
;         for (int t = 0; t < nt; t += 2) {
;             const bool last = (t == nt - 2);
;             if constexpr (Epi::HAS_MID) { if (t == E.mid_t) E.mid(acc, cur, wr, wc, fr, fq); }
;             const char* a1 = cA + (size_t)(t + 1) * kstep;
;             const char* a2 = last ? nA : cA + (size_t)(t + 2) * kstep; const char* b2 = last ? nB : cB + (size_t)(t + 2) * kstep;
;             const char* a3 = a2 + kstep; const char* b3 = b2 + kstep;
;             if (last && has_next) S.a_ready(nxt);
;             if constexpr (SP2) {
;             PG8_LDB(B0, 0, 0); PG8_LDB(B1, 0, 1); PG8_SCHED; PG8_LDA(At, 0, 0); PG8_STAGE(PG8_SA(1, 1), a1 + hstepA, voffA);
;             PG8_WAIT_V(8); PG8_WAIT_L(0); PG8_BAR; PG8_MMA(0, 0, At, B0); PG8_MMA(0, 1, At, B1); PG8_BAR; PG8_SCHED;
;             PG8_LDA(At, 0, 1); PG8_STAGE(PG8_SB(0, 0), b2, voffB); PG8_STAGE(PG8_SB(0, 1), b2 + hstepB, voffB); PG8_STAGE(PG8_SA(0, 0), a2, voffA);
;             PG8_WAIT_V(8); PG8_WAIT_L(0); PG8_BAR; PG8_MMA(1, 0, At, B0); PG8_MMA(1, 1, At, B1); PG8_BAR; PG8_SCHED;
;             PG8_LDB(B0, 1, 0); PG8_LDB(B1, 1, 1); PG8_SCHED; PG8_LDA(At, 1, 0); PG8_STAGE(PG8_SA(0, 1), a2 + hstepA, voffA);
;             PG8_WAIT_V(8); PG8_WAIT_L(0); PG8_BAR; PG8_MMA(0, 0, At, B0); PG8_MMA(0, 1, At, B1); PG8_BAR; PG8_SCHED;
.Lp7h_loop:
	ds_read_b128 v[144:147], v151
	ds_read_b128 v[156:159], v151 offset:1024
	ds_read_b128 v[160:163], v151 offset:2048
	ds_read_b128 v[164:167], v151 offset:3072
	ds_read_b128 v[168:171], v152
	ds_read_b128 v[172:175], v152 offset:1024
	ds_read_b128 v[176:179], v152 offset:2048
	ds_read_b128 v[180:183], v152 offset:3072
	s_add_u32 s34, s30, 0xfff80080
	s_addc_u32 s35, s31, -1
	s_cmp_eq_u32 s62, 28
	s_cselect_b32 s39, s21, s35
	s_cselect_b32 s38, s25, s34
	s_cselect_b32 s35, s23, s61
	s_cselect_b32 s34, s59, s60
	v_lshl_add_u64 v[216:217], s[30:31], 0, v[136:137]
	s_add_i32 m0, s6, 0xc000
	s_nop 0
	global_load_lds_dwordx4 v[216:217], off
	v_lshl_add_u64 v[216:217], s[30:31], 0, v[138:139]
	s_add_i32 m0, s6, 0xe000
	s_nop 0
	global_load_lds_dwordx4 v[216:217], off
	s_waitcnt vmcnt(6)
	s_waitcnt lgkmcnt(0)
	s_barrier
	s_setprio 1
	s_waitcnt lgkmcnt(0)
	v_mfma_f32_16x16x32_bf16 v[56:59], v[80:83], v[184:187], v[56:59]
	v_mfma_f32_16x16x32_bf16 v[48:51], v[88:91], v[184:187], v[48:51]
	v_mfma_f32_16x16x32_bf16 v[40:43], v[80:83], v[192:195], v[40:43]
	v_mfma_f32_16x16x32_bf16 v[32:35], v[88:91], v[192:195], v[32:35]
	v_mfma_f32_16x16x32_bf16 v[24:27], v[80:83], v[200:203], v[24:27]
	v_mfma_f32_16x16x32_bf16 v[16:19], v[88:91], v[200:203], v[16:19]
	v_mfma_f32_16x16x32_bf16 v[8:11], v[80:83], v[208:211], v[8:11]
	v_mfma_f32_16x16x32_bf16 v[0:3], v[88:91], v[208:211], v[0:3]
	v_mfma_f32_16x16x32_bf16 v[56:59], v[84:87], v[188:191], v[56:59]
	v_mfma_f32_16x16x32_bf16 v[48:51], v[92:95], v[188:191], v[48:51]
	v_mfma_f32_16x16x32_bf16 v[40:43], v[84:87], v[196:199], v[40:43]
	v_mfma_f32_16x16x32_bf16 v[32:35], v[92:95], v[196:199], v[32:35]
	v_mfma_f32_16x16x32_bf16 v[24:27], v[84:87], v[204:207], v[24:27]
	v_mfma_f32_16x16x32_bf16 v[16:19], v[92:95], v[204:207], v[16:19]
	v_mfma_f32_16x16x32_bf16 v[8:11], v[84:87], v[212:215], v[8:11]
	v_mfma_f32_16x16x32_bf16 v[0:3], v[92:95], v[212:215], v[0:3]
	s_setprio 0
	s_setprio 1
	s_setprio 0
	s_barrier
	s_add_i32 s63, s53, s4
	v_lshl_add_u64 v[216:217], s[34:35], 0, v[132:133]
	s_mov_b32 m0, s63
	ds_read_b128 v[184:187], v153 offset:16384
	ds_read_b128 v[188:191], v153 offset:17408
	ds_read_b128 v[192:195], v153 offset:18432
	ds_read_b128 v[196:199], v153 offset:19456
	ds_read_b128 v[200:203], v153 offset:20480
	ds_read_b128 v[204:207], v153 offset:21504
	ds_read_b128 v[208:211], v153 offset:22528
	ds_read_b128 v[212:215], v153 offset:23552
	global_load_lds_dwordx4 v[216:217], off
	s_add_i32 m0, s63, 0x2000
	s_add_u32 s64, s34, 0x80000
	v_lshl_add_u64 v[218:219], s[34:35], 0, v[128:129]
	s_addc_u32 s65, s35, 0
	s_add_i32 s63, s54, s4
	global_load_lds_dwordx4 v[218:219], off
	v_lshl_add_u64 v[220:221], s[64:65], 0, v[132:133]
	s_mov_b32 m0, s63
	v_lshl_add_u64 v[222:223], s[38:39], 0, v[130:131]
	global_load_lds_dwordx4 v[220:221], off
	v_lshl_add_u64 v[220:221], s[64:65], 0, v[128:129]
	s_add_i32 m0, s63, 0x2000
	s_nop 0
	global_load_lds_dwordx4 v[220:221], off
	v_lshl_add_u64 v[220:221], s[38:39], 0, v[134:135]
	s_mov_b32 m0, s6
	s_nop 0
	s_mov_b32 m0, s7
	s_nop 0
	s_waitcnt vmcnt(6)
	s_waitcnt lgkmcnt(0)
	s_barrier
	s_setprio 1
	s_waitcnt lgkmcnt(0)
	v_mfma_f32_16x16x32_bf16 v[60:63], v[144:147], v[184:187], v[60:63]
	v_mfma_f32_16x16x32_bf16 v[52:55], v[160:163], v[184:187], v[52:55]
	v_mfma_f32_16x16x32_bf16 v[44:47], v[144:147], v[192:195], v[44:47]
	v_mfma_f32_16x16x32_bf16 v[36:39], v[160:163], v[192:195], v[36:39]
	v_mfma_f32_16x16x32_bf16 v[28:31], v[144:147], v[200:203], v[28:31]
	v_mfma_f32_16x16x32_bf16 v[20:23], v[160:163], v[200:203], v[20:23]
	v_mfma_f32_16x16x32_bf16 v[12:15], v[144:147], v[208:211], v[12:15]
	v_mfma_f32_16x16x32_bf16 v[4:7], v[160:163], v[208:211], v[4:7]
	v_mfma_f32_16x16x32_bf16 v[60:63], v[156:159], v[188:191], v[60:63]
	v_mfma_f32_16x16x32_bf16 v[52:55], v[164:167], v[188:191], v[52:55]
	v_mfma_f32_16x16x32_bf16 v[44:47], v[156:159], v[196:199], v[44:47]
	v_mfma_f32_16x16x32_bf16 v[36:39], v[164:167], v[196:199], v[36:39]
	v_mfma_f32_16x16x32_bf16 v[28:31], v[156:159], v[204:207], v[28:31]
	v_mfma_f32_16x16x32_bf16 v[20:23], v[164:167], v[204:207], v[20:23]
	v_mfma_f32_16x16x32_bf16 v[12:15], v[156:159], v[212:215], v[12:15]
	v_mfma_f32_16x16x32_bf16 v[4:7], v[164:167], v[212:215], v[4:7]
	s_setprio 0
	s_setprio 1
	s_setprio 0
	s_barrier
	s_add_i32 s63, 0, 0x18000
	v_add_u32_e32 v155, s63, v150
	s_add_i32 s64, 0, 0x1c000
	ds_read_b128 v[64:67], v155
	ds_read_b128 v[68:71], v155 offset:1024
	ds_read_b128 v[72:75], v155 offset:2048
	ds_read_b128 v[76:79], v155 offset:3072
	v_add_u32_e32 v155, s64, v150
	ds_read_b128 v[80:83], v155
	ds_read_b128 v[84:87], v155 offset:1024
	ds_read_b128 v[88:91], v155 offset:2048
	ds_read_b128 v[92:95], v155 offset:3072
	s_add_u32 s38, s38, 0x80000
	s_addc_u32 s39, s39, 0
	s_mov_b32 m0, s41
	v_lshl_add_u64 v[224:225], s[38:39], 0, v[134:135]
	global_load_lds_dwordx4 v[224:225], off
	v_lshl_add_u64 v[224:225], s[38:39], 0, v[130:131]
	s_mov_b32 m0, s42
	s_nop 0
	global_load_lds_dwordx4 v[224:225], off
	s_waitcnt vmcnt(6)
	s_waitcnt lgkmcnt(0)
	s_barrier
; #define PG8_STAGE(bufoff, gbase, voff) do { _Pragma("unroll") for (int _i = 0; _i < 2; ++_i) \
;         __builtin_amdgcn_global_load_lds((const unsigned*)((const char*)(gbase) + (voff)[_i]), (PG8_LAS unsigned*)(lds + (bufoff) + ldsw + _i * 8192), 16, 0, 0); } while (0)
; #define PG8_LDA(dst, b, h) do { _Pragma("unroll") for (int m = 0; m < 4; ++m) _Pragma("unroll") for (int k = 0; k < 2; ++k) dst[m][k] = *(const PG8_LAS bf16x8*)(lds + PG8_SA(b, h) + aoff + m * 2048 + k * 1024); } while (0)
; #define PG8_MMA(ai, bj, At, Bt) do { __builtin_amdgcn_s_setprio(1); _Pragma("unroll") for (int m = 0; m < 4; ++m) _Pragma("unroll") for (int n = 0; n < 2; ++n) _Pragma("unroll") for (int k = 0; k < 2; ++k) \
;         acc[ai][bj][m][n] = __builtin_amdgcn_mfma_f32_16x16x32_bf16(Bt[n][k], At[m][k], acc[ai][bj][m][n], 0, 0, 0); __builtin_amdgcn_s_setprio(0); } while (0)
; #define PG8_WAIT_V(n) asm volatile("s_waitcnt vmcnt(" #n ")" ::: "memory")
; #define PG8_WAIT_L(n) asm volatile("s_waitcnt lgkmcnt(" #n ")" ::: "memory")
; #define PG8_BAR __builtin_amdgcn_s_barrier()
; #define PG8_SCHED __builtin_amdgcn_sched_barrier(0)
; template <class Epi, class Sched, bool ALIGN_EPI = false, bool SP2 = false>
; __device__ __forceinline__ void gemm_phase(PG8_LAS unsigned char* lds, const Gemm g, const Sched& S, const Epi& E) {
;     ...
;             PG8_WAIT_V(8); PG8_WAIT_L(0); PG8_BAR; PG8_MMA(0, 0, At, B0); PG8_MMA(0, 1, At, B1); PG8_BAR; PG8_SCHED;
;             PG8_LDA(At, 1, 1); PG8_STAGE(PG8_SB(1, 0), b3, voffB); PG8_STAGE(PG8_SB(1, 1), b3 + hstepB, voffB); PG8_STAGE(PG8_SA(1, 0), a3, voffA);
;             PG8_WAIT_V(8); PG8_WAIT_L(0); PG8_BAR; PG8_MMA(1, 0, At, B0); PG8_MMA(1, 1, At, B1); PG8_BAR; PG8_SCHED;
	s_setprio 1
	s_waitcnt lgkmcnt(0)
	v_mfma_f32_16x16x32_bf16 v[56:59], v[168:171], v[184:187], v[56:59]
	v_mfma_f32_16x16x32_bf16 v[48:51], v[176:179], v[184:187], v[48:51]
	v_mfma_f32_16x16x32_bf16 v[40:43], v[168:171], v[192:195], v[40:43]
	v_mfma_f32_16x16x32_bf16 v[32:35], v[176:179], v[192:195], v[32:35]
	v_mfma_f32_16x16x32_bf16 v[24:27], v[168:171], v[200:203], v[24:27]
	v_mfma_f32_16x16x32_bf16 v[16:19], v[176:179], v[200:203], v[16:19]
	v_mfma_f32_16x16x32_bf16 v[8:11], v[168:171], v[208:211], v[8:11]
	v_mfma_f32_16x16x32_bf16 v[0:3], v[176:179], v[208:211], v[0:3]
	v_mfma_f32_16x16x32_bf16 v[56:59], v[172:175], v[188:191], v[56:59]
	v_mfma_f32_16x16x32_bf16 v[48:51], v[180:183], v[188:191], v[48:51]
	v_mfma_f32_16x16x32_bf16 v[40:43], v[172:175], v[196:199], v[40:43]
	v_mfma_f32_16x16x32_bf16 v[32:35], v[180:183], v[196:199], v[32:35]
	v_mfma_f32_16x16x32_bf16 v[24:27], v[172:175], v[204:207], v[24:27]
	v_mfma_f32_16x16x32_bf16 v[16:19], v[180:183], v[204:207], v[16:19]
	v_mfma_f32_16x16x32_bf16 v[8:11], v[172:175], v[212:215], v[8:11]
	v_mfma_f32_16x16x32_bf16 v[0:3], v[180:183], v[212:215], v[0:3]
	s_setprio 0
	s_setprio 1
	s_setprio 0
	s_barrier
	s_add_i32 s38, s63, s4
	v_lshl_add_u64 v[216:217], v[216:217], 0, s[16:17]
	s_mov_b32 m0, s38
	ds_read_b128 v[184:187], v153 offset:49152
	ds_read_b128 v[188:191], v153 offset:50176
	ds_read_b128 v[192:195], v153 offset:51200
	ds_read_b128 v[196:199], v153 offset:52224
	ds_read_b128 v[200:203], v153 offset:53248
	ds_read_b128 v[204:207], v153 offset:54272
	ds_read_b128 v[208:211], v153 offset:55296
	ds_read_b128 v[212:215], v153 offset:56320
	global_load_lds_dwordx4 v[216:217], off
	s_add_i32 m0, s38, 0x2000
	s_add_u32 s34, s34, 0x80080
	v_lshl_add_u64 v[216:217], v[218:219], 0, s[16:17]
	s_addc_u32 s35, s35, 0
	s_add_i32 s38, s64, s4
	global_load_lds_dwordx4 v[216:217], off
	v_lshl_add_u64 v[216:217], s[34:35], 0, v[132:133]
	s_mov_b32 m0, s38
	s_nop 0
	global_load_lds_dwordx4 v[216:217], off
	v_lshl_add_u64 v[216:217], s[34:35], 0, v[128:129]
	s_add_i32 m0, s38, 0x2000
	s_nop 0
	global_load_lds_dwordx4 v[216:217], off
	v_lshl_add_u64 v[216:217], v[220:221], 0, s[16:17]
	s_mov_b32 m0, s46
	s_nop 0
	v_lshl_add_u64 v[216:217], v[222:223], 0, s[16:17]
	s_mov_b32 m0, s47
	s_nop 0
	s_waitcnt vmcnt(6)
	s_waitcnt lgkmcnt(0)
	s_barrier
	s_setprio 1
	s_waitcnt lgkmcnt(0)
	v_mfma_f32_16x16x32_bf16 v[60:63], v[64:67], v[184:187], v[60:63]
	v_mfma_f32_16x16x32_bf16 v[52:55], v[72:75], v[184:187], v[52:55]
	v_mfma_f32_16x16x32_bf16 v[44:47], v[64:67], v[192:195], v[44:47]
	v_mfma_f32_16x16x32_bf16 v[36:39], v[72:75], v[192:195], v[36:39]
	v_mfma_f32_16x16x32_bf16 v[28:31], v[64:67], v[200:203], v[28:31]
	v_mfma_f32_16x16x32_bf16 v[20:23], v[72:75], v[200:203], v[20:23]
	v_mfma_f32_16x16x32_bf16 v[12:15], v[64:67], v[208:211], v[12:15]
	v_mfma_f32_16x16x32_bf16 v[4:7], v[72:75], v[208:211], v[4:7]
	v_mfma_f32_16x16x32_bf16 v[60:63], v[68:71], v[188:191], v[60:63]
	v_mfma_f32_16x16x32_bf16 v[52:55], v[76:79], v[188:191], v[52:55]
	v_mfma_f32_16x16x32_bf16 v[44:47], v[68:71], v[196:199], v[44:47]
	v_mfma_f32_16x16x32_bf16 v[36:39], v[76:79], v[196:199], v[36:39]
	v_mfma_f32_16x16x32_bf16 v[28:31], v[68:71], v[204:207], v[28:31]
	v_mfma_f32_16x16x32_bf16 v[20:23], v[76:79], v[204:207], v[20:23]
	v_mfma_f32_16x16x32_bf16 v[12:15], v[68:71], v[212:215], v[12:15]
	v_mfma_f32_16x16x32_bf16 v[4:7], v[76:79], v[212:215], v[4:7]
	s_setprio 0
	s_setprio 1
	s_setprio 0
	s_barrier
	s_add_i32 s62, s62, 2
	s_add_u32 s30, s30, 0x100
	s_addc_u32 s31, s31, 0
	s_add_u32 s60, s60, 0x100
	s_addc_u32 s61, s61, 0
	s_cmp_gt_u32 s62, 29
	s_cbranch_scc0 .Lp7h_loop
	v_mfma_f32_16x16x32_bf16 v[56:59], v[80:83], v[184:187], v[56:59]
	v_mfma_f32_16x16x32_bf16 v[48:51], v[88:91], v[184:187], v[48:51]
	v_mfma_f32_16x16x32_bf16 v[40:43], v[80:83], v[192:195], v[40:43]
	v_mfma_f32_16x16x32_bf16 v[32:35], v[88:91], v[192:195], v[32:35]
	v_mfma_f32_16x16x32_bf16 v[24:27], v[80:83], v[200:203], v[24:27]
	v_mfma_f32_16x16x32_bf16 v[16:19], v[88:91], v[200:203], v[16:19]
	v_mfma_f32_16x16x32_bf16 v[8:11], v[80:83], v[208:211], v[8:11]
	v_mfma_f32_16x16x32_bf16 v[0:3], v[88:91], v[208:211], v[0:3]
	v_mfma_f32_16x16x32_bf16 v[56:59], v[84:87], v[188:191], v[56:59]
	v_mfma_f32_16x16x32_bf16 v[48:51], v[92:95], v[188:191], v[48:51]
	v_mfma_f32_16x16x32_bf16 v[40:43], v[84:87], v[196:199], v[40:43]
	v_mfma_f32_16x16x32_bf16 v[32:35], v[92:95], v[196:199], v[32:35]
	v_mfma_f32_16x16x32_bf16 v[24:27], v[84:87], v[204:207], v[24:27]
	v_mfma_f32_16x16x32_bf16 v[16:19], v[92:95], v[204:207], v[16:19]
	v_mfma_f32_16x16x32_bf16 v[8:11], v[84:87], v[212:215], v[8:11]
	v_mfma_f32_16x16x32_bf16 v[0:3], v[92:95], v[212:215], v[0:3]
	s_nop 15
	s_nop 15
	s_branch .Lp7_after_loop

; #define PG8_STAGE(bufoff, gbase, voff) do { _Pragma("unroll") for (int _i = 0; _i < 2; ++_i) \
;         __builtin_amdgcn_global_load_lds((const unsigned*)((const char*)(gbase) + (voff)[_i]), (PG8_LAS unsigned*)(lds + (bufoff) + ldsw + _i * 8192), 16, 0, 0); } while (0)
; #define PG8_LDA(dst, b, h) do { _Pragma("unroll") for (int m = 0; m < 4; ++m) _Pragma("unroll") for (int k = 0; k < 2; ++k) dst[m][k] = *(const PG8_LAS bf16x8*)(lds + PG8_SA(b, h) + aoff + m * 2048 + k * 1024); } while (0)
; #define PG8_LDB(dst, b, h) do { _Pragma("unroll") for (int n = 0; n < 2; ++n) _Pragma("unroll") for (int k = 0; k < 2; ++k) dst[n][k] = *(const PG8_LAS bf16x8*)(lds + PG8_SB(b, h) + boff + n * 2048 + k * 1024); } while (0)
; #define PG8_WAIT_V(n) asm volatile("s_waitcnt vmcnt(" #n ")" ::: "memory")
; #define PG8_WAIT_L(n) asm volatile("s_waitcnt lgkmcnt(" #n ")" ::: "memory")
; #define PG8_BAR __builtin_amdgcn_s_barrier()
; #define PG8_SCHED __builtin_amdgcn_sched_barrier(0)
; template <class Epi, class Sched, bool ALIGN_EPI = false, bool SP2 = false>
; __device__ __forceinline__ void gemm_phase(PG8_LAS unsigned char* lds, const Gemm g, const Sched& S, const Epi& E) {
;     ...
;         const char* nA = has_next ? (const char*)g.A + (size_t)nxt.pm * tstepA : cA; const char* nB = has_next ? (const char*)g.Bt + (size_t)nxt.pn * tstepB : cB;
;         for (int t = 0; t < nt; t += 2) {
;             const bool last = (t == nt - 2);
;             if constexpr (Epi::HAS_MID) { if (t == E.mid_t) E.mid(acc, cur, wr, wc, fr, fq); }
;             const char* a1 = cA + (size_t)(t + 1) * kstep;
;             const char* a2 = last ? nA : cA + (size_t)(t + 2) * kstep; const char* b2 = last ? nB : cB + (size_t)(t + 2) * kstep;
;             const char* a3 = a2 + kstep; const char* b3 = b2 + kstep;
;             if (last && has_next) S.a_ready(nxt);
;             if constexpr (SP2) {
;             PG8_LDB(B0, 0, 0); PG8_LDB(B1, 0, 1); PG8_SCHED; PG8_LDA(At, 0, 0); PG8_STAGE(PG8_SA(1, 1), a1 + hstepA, voffA);
;             PG8_WAIT_V(8); PG8_WAIT_L(0); PG8_BAR; PG8_MMA(0, 0, At, B0); PG8_MMA(0, 1, At, B1); PG8_BAR; PG8_SCHED;
;             PG8_LDA(At, 0, 1); PG8_STAGE(PG8_SB(0, 0), b2, voffB); PG8_STAGE(PG8_SB(0, 1), b2 + hstepB, voffB); PG8_STAGE(PG8_SA(0, 0), a2, voffA);
;             PG8_WAIT_V(8); PG8_WAIT_L(0); PG8_BAR; PG8_MMA(1, 0, At, B0); PG8_MMA(1, 1, At, B1); PG8_BAR; PG8_SCHED;
.LBB0_1912:
	ds_read_b128 v[144:147], v151
	ds_read_b128 v[154:157], v151 offset:1024
	ds_read_b128 v[158:161], v151 offset:2048
	ds_read_b128 v[162:165], v151 offset:3072
	ds_read_b128 v[166:169], v152
	ds_read_b128 v[170:173], v152 offset:1024
	ds_read_b128 v[174:177], v152 offset:2048
	ds_read_b128 v[178:181], v152 offset:3072
	s_add_u32 s4, s40, 0x100
	s_addc_u32 s5, s41, 0
	s_cmpk_eq_i32 s65, 0x54
	s_cselect_b32 s47, s35, s5
	s_cselect_b32 s46, s34, s4
	s_cselect_b32 s43, s37, s64
	s_cselect_b32 s42, s36, s39
	v_lshl_add_u64 v[214:215], s[40:41], 0, v[136:137]
	s_add_i32 m0, s50, 0xc000
	ds_read_b128 v[182:185], v153
	ds_read_b128 v[186:189], v153 offset:1024
	ds_read_b128 v[190:193], v153 offset:2048
	ds_read_b128 v[194:197], v153 offset:3072
	ds_read_b128 v[198:201], v153 offset:4096
	ds_read_b128 v[202:205], v153 offset:5120
	ds_read_b128 v[206:209], v153 offset:6144
	ds_read_b128 v[210:213], v153 offset:7168
	s_add_u32 s98, s40, 0x80
	s_addc_u32 s99, s41, 0
	s_mov_b32 m0, s55
	s_nop 0
	global_load_lds_dwordx4 v128, s[98:99]
	s_mov_b32 m0, s56
	s_nop 0
	global_load_lds_dwordx4 v132, s[98:99]
	s_add_i32 m0, s50, 0xc000
	s_nop 0
	global_load_lds_dwordx4 v[214:215], off
	v_lshl_add_u64 v[214:215], s[40:41], 0, v[138:139]
	s_add_i32 m0, s50, 0xe000
	s_nop 0
	global_load_lds_dwordx4 v[214:215], off
	s_waitcnt vmcnt(8)
	s_waitcnt lgkmcnt(0)
	s_barrier
	s_setprio 1
	s_waitcnt lgkmcnt(0)
	v_mfma_f32_16x16x32_bf16 v[120:123], v[144:147], v[182:185], v[120:123]
	v_mfma_f32_16x16x32_bf16 v[124:127], v[158:161], v[182:185], v[124:127]
	v_mfma_f32_16x16x32_bf16 v[104:107], v[144:147], v[190:193], v[104:107]
	v_mfma_f32_16x16x32_bf16 v[108:111], v[158:161], v[190:193], v[108:111]
	v_mfma_f32_16x16x32_bf16 v[88:91], v[144:147], v[198:201], v[88:91]
	v_mfma_f32_16x16x32_bf16 v[92:95], v[158:161], v[198:201], v[92:95]
	v_mfma_f32_16x16x32_bf16 v[72:75], v[144:147], v[206:209], v[72:75]
	v_mfma_f32_16x16x32_bf16 v[76:79], v[158:161], v[206:209], v[76:79]
	v_mfma_f32_16x16x32_bf16 v[120:123], v[154:157], v[186:189], v[120:123]
	v_mfma_f32_16x16x32_bf16 v[124:127], v[162:165], v[186:189], v[124:127]
	v_mfma_f32_16x16x32_bf16 v[104:107], v[154:157], v[194:197], v[104:107]
	v_mfma_f32_16x16x32_bf16 v[108:111], v[162:165], v[194:197], v[108:111]
	v_mfma_f32_16x16x32_bf16 v[88:91], v[154:157], v[202:205], v[88:91]
	v_mfma_f32_16x16x32_bf16 v[92:95], v[162:165], v[202:205], v[92:95]
	v_mfma_f32_16x16x32_bf16 v[72:75], v[154:157], v[210:213], v[72:75]
	v_mfma_f32_16x16x32_bf16 v[76:79], v[162:165], v[210:213], v[76:79]
	s_setprio 0
	s_setprio 1
	v_mfma_f32_16x16x32_bf16 v[112:115], v[166:169], v[182:185], v[112:115]
	v_mfma_f32_16x16x32_bf16 v[116:119], v[174:177], v[182:185], v[116:119]
	v_mfma_f32_16x16x32_bf16 v[96:99], v[166:169], v[190:193], v[96:99]
	v_mfma_f32_16x16x32_bf16 v[100:103], v[174:177], v[190:193], v[100:103]
	v_mfma_f32_16x16x32_bf16 v[80:83], v[166:169], v[198:201], v[80:83]
	v_mfma_f32_16x16x32_bf16 v[84:87], v[174:177], v[198:201], v[84:87]
	v_mfma_f32_16x16x32_bf16 v[64:67], v[166:169], v[206:209], v[64:67]
	v_mfma_f32_16x16x32_bf16 v[68:71], v[174:177], v[206:209], v[68:71]
	v_mfma_f32_16x16x32_bf16 v[112:115], v[170:173], v[186:189], v[112:115]
	v_mfma_f32_16x16x32_bf16 v[116:119], v[178:181], v[186:189], v[116:119]
	v_mfma_f32_16x16x32_bf16 v[96:99], v[170:173], v[194:197], v[96:99]
	v_mfma_f32_16x16x32_bf16 v[100:103], v[178:181], v[194:197], v[100:103]
	v_mfma_f32_16x16x32_bf16 v[80:83], v[170:173], v[202:205], v[80:83]
	v_mfma_f32_16x16x32_bf16 v[84:87], v[178:181], v[202:205], v[84:87]
	v_mfma_f32_16x16x32_bf16 v[64:67], v[170:173], v[210:213], v[64:67]
	v_mfma_f32_16x16x32_bf16 v[68:71], v[178:181], v[210:213], v[68:71]
	s_setprio 0
	s_barrier
	s_add_i32 s40, s58, s33
	v_lshl_add_u64 v[214:215], s[42:43], 0, v[130:131]
	s_mov_b32 m0, s40
	ds_read_b128 v[182:185], v153 offset:16384
	ds_read_b128 v[186:189], v153 offset:17408
	ds_read_b128 v[190:193], v153 offset:18432
	ds_read_b128 v[194:197], v153 offset:19456
	ds_read_b128 v[198:201], v153 offset:20480
	ds_read_b128 v[202:205], v153 offset:21504
	ds_read_b128 v[206:209], v153 offset:22528
	ds_read_b128 v[210:213], v153 offset:23552
	global_load_lds_dwordx4 v[214:215], off
	s_add_i32 m0, s40, 0x2000
	s_add_u32 s40, s42, 0x160000
	v_lshl_add_u64 v[216:217], s[42:43], 0, v[134:135]
	s_addc_u32 s41, s43, 0
	s_add_i32 s66, s59, s33
	global_load_lds_dwordx4 v[216:217], off
	v_lshl_add_u64 v[218:219], s[40:41], 0, v[130:131]
	s_mov_b32 m0, s66
	s_nop 0
	global_load_lds_dwordx4 v[218:219], off
	v_lshl_add_u64 v[218:219], s[40:41], 0, v[134:135]
	s_add_i32 m0, s66, 0x2000
	s_nop 0
	global_load_lds_dwordx4 v[218:219], off
	s_waitcnt vmcnt(6)
	s_waitcnt lgkmcnt(0)
	s_barrier
; #define PG8_STAGE(bufoff, gbase, voff) do { _Pragma("unroll") for (int _i = 0; _i < 2; ++_i) \
;         __builtin_amdgcn_global_load_lds((const unsigned*)((const char*)(gbase) + (voff)[_i]), (PG8_LAS unsigned*)(lds + (bufoff) + ldsw + _i * 8192), 16, 0, 0); } while (0)
; #define PG8_LDA(dst, b, h) do { _Pragma("unroll") for (int m = 0; m < 4; ++m) _Pragma("unroll") for (int k = 0; k < 2; ++k) dst[m][k] = *(const PG8_LAS bf16x8*)(lds + PG8_SA(b, h) + aoff + m * 2048 + k * 1024); } while (0)
; #define PG8_LDB(dst, b, h) do { _Pragma("unroll") for (int n = 0; n < 2; ++n) _Pragma("unroll") for (int k = 0; k < 2; ++k) dst[n][k] = *(const PG8_LAS bf16x8*)(lds + PG8_SB(b, h) + boff + n * 2048 + k * 1024); } while (0)
; #define PG8_MMA(ai, bj, At, Bt) do { __builtin_amdgcn_s_setprio(1); _Pragma("unroll") for (int m = 0; m < 4; ++m) _Pragma("unroll") for (int n = 0; n < 2; ++n) _Pragma("unroll") for (int k = 0; k < 2; ++k) \
;         acc[ai][bj][m][n] = __builtin_amdgcn_mfma_f32_16x16x32_bf16(Bt[n][k], At[m][k], acc[ai][bj][m][n], 0, 0, 0); __builtin_amdgcn_s_setprio(0); } while (0)
; #define PG8_WAIT_V(n) asm volatile("s_waitcnt vmcnt(" #n ")" ::: "memory")
; #define PG8_WAIT_L(n) asm volatile("s_waitcnt lgkmcnt(" #n ")" ::: "memory")
; #define PG8_BAR __builtin_amdgcn_s_barrier()
; #define PG8_SCHED __builtin_amdgcn_sched_barrier(0)
; template <class Epi, class Sched, bool ALIGN_EPI = false, bool SP2 = false>
; __device__ __forceinline__ void gemm_phase(PG8_LAS unsigned char* lds, const Gemm g, const Sched& S, const Epi& E) {
;     ...
;             PG8_WAIT_V(8); PG8_WAIT_L(0); PG8_BAR; PG8_MMA(1, 0, At, B0); PG8_MMA(1, 1, At, B1); PG8_BAR; PG8_SCHED;
;             PG8_LDB(B0, 1, 0); PG8_LDB(B1, 1, 1); PG8_SCHED; PG8_LDA(At, 1, 0); PG8_STAGE(PG8_SA(0, 1), a2 + hstepA, voffA);
;             PG8_WAIT_V(8); PG8_WAIT_L(0); PG8_BAR; PG8_MMA(0, 0, At, B0); PG8_MMA(0, 1, At, B1); PG8_BAR; PG8_SCHED;
	s_setprio 1
	s_waitcnt lgkmcnt(0)
	v_mfma_f32_16x16x32_bf16 v[56:59], v[144:147], v[182:185], v[56:59]
	v_mfma_f32_16x16x32_bf16 v[60:63], v[158:161], v[182:185], v[60:63]
	v_mfma_f32_16x16x32_bf16 v[40:43], v[144:147], v[190:193], v[40:43]
	v_mfma_f32_16x16x32_bf16 v[44:47], v[158:161], v[190:193], v[44:47]
	v_mfma_f32_16x16x32_bf16 v[24:27], v[144:147], v[198:201], v[24:27]
	v_mfma_f32_16x16x32_bf16 v[28:31], v[158:161], v[198:201], v[28:31]
	v_mfma_f32_16x16x32_bf16 v[8:11], v[144:147], v[206:209], v[8:11]
	v_mfma_f32_16x16x32_bf16 v[12:15], v[158:161], v[206:209], v[12:15]
	v_mfma_f32_16x16x32_bf16 v[56:59], v[154:157], v[186:189], v[56:59]
	v_mfma_f32_16x16x32_bf16 v[60:63], v[162:165], v[186:189], v[60:63]
	v_mfma_f32_16x16x32_bf16 v[40:43], v[154:157], v[194:197], v[40:43]
	v_mfma_f32_16x16x32_bf16 v[44:47], v[162:165], v[194:197], v[44:47]
	v_mfma_f32_16x16x32_bf16 v[24:27], v[154:157], v[202:205], v[24:27]
	v_mfma_f32_16x16x32_bf16 v[28:31], v[162:165], v[202:205], v[28:31]
	v_mfma_f32_16x16x32_bf16 v[8:11], v[154:157], v[210:213], v[8:11]
	v_mfma_f32_16x16x32_bf16 v[12:15], v[162:165], v[210:213], v[12:15]
	s_setprio 0
	s_setprio 1
	v_mfma_f32_16x16x32_bf16 v[48:51], v[166:169], v[182:185], v[48:51]
	v_mfma_f32_16x16x32_bf16 v[52:55], v[174:177], v[182:185], v[52:55]
	v_mfma_f32_16x16x32_bf16 v[32:35], v[166:169], v[190:193], v[32:35]
	v_mfma_f32_16x16x32_bf16 v[36:39], v[174:177], v[190:193], v[36:39]
	v_mfma_f32_16x16x32_bf16 v[16:19], v[166:169], v[198:201], v[16:19]
	v_mfma_f32_16x16x32_bf16 v[20:23], v[174:177], v[198:201], v[20:23]
	v_mfma_f32_16x16x32_bf16 v[4:7], v[166:169], v[206:209], v[4:7]
	v_mfma_f32_16x16x32_bf16 v[0:3], v[174:177], v[206:209], v[0:3]
	v_mfma_f32_16x16x32_bf16 v[48:51], v[170:173], v[186:189], v[48:51]
	v_mfma_f32_16x16x32_bf16 v[52:55], v[178:181], v[186:189], v[52:55]
	v_mfma_f32_16x16x32_bf16 v[32:35], v[170:173], v[194:197], v[32:35]
	v_mfma_f32_16x16x32_bf16 v[36:39], v[178:181], v[194:197], v[36:39]
	v_mfma_f32_16x16x32_bf16 v[16:19], v[170:173], v[202:205], v[16:19]
	v_mfma_f32_16x16x32_bf16 v[20:23], v[178:181], v[202:205], v[20:23]
	v_mfma_f32_16x16x32_bf16 v[4:7], v[170:173], v[210:213], v[4:7]
	v_mfma_f32_16x16x32_bf16 v[0:3], v[178:181], v[210:213], v[0:3]
	s_setprio 0
	s_barrier
	s_add_i32 s66, 0, 0x18000
	s_add_i32 s67, 0, 0x1c000
	v_add_u32_e32 v162, s66, v150
	v_add_u32_e32 v178, s67, v150
	ds_read_b128 v[144:147], v162
	ds_read_b128 v[154:157], v162 offset:1024
	ds_read_b128 v[158:161], v162 offset:2048
	ds_read_b128 v[162:165], v162 offset:3072
	ds_read_b128 v[166:169], v178
	ds_read_b128 v[170:173], v178 offset:1024
	ds_read_b128 v[174:177], v178 offset:2048
	ds_read_b128 v[178:181], v178 offset:3072
	s_add_u32 s40, s46, 0x160000
	s_addc_u32 s41, s47, 0
	s_mov_b32 m0, s52
	v_lshl_add_u64 v[222:223], s[40:41], 0, v[128:129]
	ds_read_b128 v[182:185], v153 offset:32768
	ds_read_b128 v[186:189], v153 offset:33792
	ds_read_b128 v[190:193], v153 offset:34816
	ds_read_b128 v[194:197], v153 offset:35840
	ds_read_b128 v[198:201], v153 offset:36864
	ds_read_b128 v[202:205], v153 offset:37888
	ds_read_b128 v[206:209], v153 offset:38912
	ds_read_b128 v[210:213], v153 offset:39936
	s_mov_b32 m0, s50
	s_nop 0
	global_load_lds_dwordx4 v128, s[46:47]
	s_mov_b32 m0, s51
	s_nop 0
	global_load_lds_dwordx4 v132, s[46:47]
	s_mov_b32 m0, s52
	s_nop 0
	global_load_lds_dwordx4 v[222:223], off
	v_lshl_add_u64 v[222:223], s[40:41], 0, v[132:133]
	s_mov_b32 m0, s53
	s_nop 0
	global_load_lds_dwordx4 v[222:223], off
	s_waitcnt vmcnt(8)
	s_waitcnt lgkmcnt(0)
	s_barrier
; #define PG8_STAGE(bufoff, gbase, voff) do { _Pragma("unroll") for (int _i = 0; _i < 2; ++_i) \
;         __builtin_amdgcn_global_load_lds((const unsigned*)((const char*)(gbase) + (voff)[_i]), (PG8_LAS unsigned*)(lds + (bufoff) + ldsw + _i * 8192), 16, 0, 0); } while (0)
; #define PG8_LDA(dst, b, h) do { _Pragma("unroll") for (int m = 0; m < 4; ++m) _Pragma("unroll") for (int k = 0; k < 2; ++k) dst[m][k] = *(const PG8_LAS bf16x8*)(lds + PG8_SA(b, h) + aoff + m * 2048 + k * 1024); } while (0)
; #define PG8_MMA(ai, bj, At, Bt) do { __builtin_amdgcn_s_setprio(1); _Pragma("unroll") for (int m = 0; m < 4; ++m) _Pragma("unroll") for (int n = 0; n < 2; ++n) _Pragma("unroll") for (int k = 0; k < 2; ++k) \
;         acc[ai][bj][m][n] = __builtin_amdgcn_mfma_f32_16x16x32_bf16(Bt[n][k], At[m][k], acc[ai][bj][m][n], 0, 0, 0); __builtin_amdgcn_s_setprio(0); } while (0)
; #define PG8_WAIT_V(n) asm volatile("s_waitcnt vmcnt(" #n ")" ::: "memory")
; #define PG8_WAIT_L(n) asm volatile("s_waitcnt lgkmcnt(" #n ")" ::: "memory")
; #define PG8_BAR __builtin_amdgcn_s_barrier()
; #define PG8_SCHED __builtin_amdgcn_sched_barrier(0)
; template <class Epi, class Sched, bool ALIGN_EPI = false, bool SP2 = false>
; __device__ __forceinline__ void gemm_phase(PG8_LAS unsigned char* lds, const Gemm g, const Sched& S, const Epi& E) {
;     ...
;             PG8_WAIT_V(8); PG8_WAIT_L(0); PG8_BAR; PG8_MMA(0, 0, At, B0); PG8_MMA(0, 1, At, B1); PG8_BAR; PG8_SCHED;
;             PG8_LDA(At, 1, 1); PG8_STAGE(PG8_SB(1, 0), b3, voffB); PG8_STAGE(PG8_SB(1, 1), b3 + hstepB, voffB); PG8_STAGE(PG8_SA(1, 0), a3, voffA);
;             PG8_WAIT_V(8); PG8_WAIT_L(0); PG8_BAR; PG8_MMA(1, 0, At, B0); PG8_MMA(1, 1, At, B1); PG8_BAR; PG8_SCHED;
;     ...
;         if constexpr (ALIGN_EPI) { if (wr == 0) PG8_BAR; }
	s_setprio 1
	s_waitcnt lgkmcnt(0)
	v_mfma_f32_16x16x32_bf16 v[120:123], v[144:147], v[182:185], v[120:123]
	v_mfma_f32_16x16x32_bf16 v[124:127], v[158:161], v[182:185], v[124:127]
	v_mfma_f32_16x16x32_bf16 v[104:107], v[144:147], v[190:193], v[104:107]
	v_mfma_f32_16x16x32_bf16 v[108:111], v[158:161], v[190:193], v[108:111]
	v_mfma_f32_16x16x32_bf16 v[88:91], v[144:147], v[198:201], v[88:91]
	v_mfma_f32_16x16x32_bf16 v[92:95], v[158:161], v[198:201], v[92:95]
	v_mfma_f32_16x16x32_bf16 v[72:75], v[144:147], v[206:209], v[72:75]
	v_mfma_f32_16x16x32_bf16 v[76:79], v[158:161], v[206:209], v[76:79]
	v_mfma_f32_16x16x32_bf16 v[120:123], v[154:157], v[186:189], v[120:123]
	v_mfma_f32_16x16x32_bf16 v[124:127], v[162:165], v[186:189], v[124:127]
	v_mfma_f32_16x16x32_bf16 v[104:107], v[154:157], v[194:197], v[104:107]
	v_mfma_f32_16x16x32_bf16 v[108:111], v[162:165], v[194:197], v[108:111]
	v_mfma_f32_16x16x32_bf16 v[88:91], v[154:157], v[202:205], v[88:91]
	v_mfma_f32_16x16x32_bf16 v[92:95], v[162:165], v[202:205], v[92:95]
	v_mfma_f32_16x16x32_bf16 v[72:75], v[154:157], v[210:213], v[72:75]
	v_mfma_f32_16x16x32_bf16 v[76:79], v[162:165], v[210:213], v[76:79]
	s_setprio 0
	s_setprio 1
	v_mfma_f32_16x16x32_bf16 v[112:115], v[166:169], v[182:185], v[112:115]
	v_mfma_f32_16x16x32_bf16 v[116:119], v[174:177], v[182:185], v[116:119]
	v_mfma_f32_16x16x32_bf16 v[96:99], v[166:169], v[190:193], v[96:99]
	v_mfma_f32_16x16x32_bf16 v[100:103], v[174:177], v[190:193], v[100:103]
	v_mfma_f32_16x16x32_bf16 v[80:83], v[166:169], v[198:201], v[80:83]
	v_mfma_f32_16x16x32_bf16 v[84:87], v[174:177], v[198:201], v[84:87]
	v_mfma_f32_16x16x32_bf16 v[64:67], v[166:169], v[206:209], v[64:67]
	v_mfma_f32_16x16x32_bf16 v[68:71], v[174:177], v[206:209], v[68:71]
	v_mfma_f32_16x16x32_bf16 v[112:115], v[170:173], v[186:189], v[112:115]
	v_mfma_f32_16x16x32_bf16 v[116:119], v[178:181], v[186:189], v[116:119]
	v_mfma_f32_16x16x32_bf16 v[96:99], v[170:173], v[194:197], v[96:99]
	v_mfma_f32_16x16x32_bf16 v[100:103], v[178:181], v[194:197], v[100:103]
	v_mfma_f32_16x16x32_bf16 v[80:83], v[170:173], v[202:205], v[80:83]
	v_mfma_f32_16x16x32_bf16 v[84:87], v[178:181], v[202:205], v[84:87]
	v_mfma_f32_16x16x32_bf16 v[64:67], v[170:173], v[210:213], v[64:67]
	v_mfma_f32_16x16x32_bf16 v[68:71], v[178:181], v[210:213], v[68:71]
	s_setprio 0
	s_barrier
	s_add_i32 s40, s66, s33
	v_lshl_add_u64 v[214:215], v[214:215], 0, s[12:13]
	s_mov_b32 m0, s40
	ds_read_b128 v[182:185], v153 offset:49152
	ds_read_b128 v[186:189], v153 offset:50176
	ds_read_b128 v[190:193], v153 offset:51200
	ds_read_b128 v[194:197], v153 offset:52224
	ds_read_b128 v[198:201], v153 offset:53248
	ds_read_b128 v[202:205], v153 offset:54272
	ds_read_b128 v[206:209], v153 offset:55296
	ds_read_b128 v[210:213], v153 offset:56320
	global_load_lds_dwordx4 v[214:215], off
	s_add_i32 m0, s40, 0x2000
	s_add_u32 s40, s42, 0x160080
	v_lshl_add_u64 v[214:215], v[216:217], 0, s[12:13]
	s_addc_u32 s41, s43, 0
	s_add_i32 s42, s67, s33
	global_load_lds_dwordx4 v[214:215], off
	v_lshl_add_u64 v[214:215], s[40:41], 0, v[130:131]
	s_mov_b32 m0, s42
	s_nop 0
	global_load_lds_dwordx4 v[214:215], off
	v_lshl_add_u64 v[214:215], s[40:41], 0, v[134:135]
	s_add_i32 m0, s42, 0x2000
	s_nop 0
	global_load_lds_dwordx4 v[214:215], off
	s_waitcnt vmcnt(6)
	s_waitcnt lgkmcnt(0)
	s_barrier
	s_setprio 1
	s_waitcnt lgkmcnt(0)
	v_mfma_f32_16x16x32_bf16 v[56:59], v[144:147], v[182:185], v[56:59]
	v_mfma_f32_16x16x32_bf16 v[60:63], v[158:161], v[182:185], v[60:63]
	v_mfma_f32_16x16x32_bf16 v[40:43], v[144:147], v[190:193], v[40:43]
	v_mfma_f32_16x16x32_bf16 v[44:47], v[158:161], v[190:193], v[44:47]
	v_mfma_f32_16x16x32_bf16 v[24:27], v[144:147], v[198:201], v[24:27]
	v_mfma_f32_16x16x32_bf16 v[28:31], v[158:161], v[198:201], v[28:31]
	v_mfma_f32_16x16x32_bf16 v[8:11], v[144:147], v[206:209], v[8:11]
	v_mfma_f32_16x16x32_bf16 v[12:15], v[158:161], v[206:209], v[12:15]
	v_mfma_f32_16x16x32_bf16 v[56:59], v[154:157], v[186:189], v[56:59]
	v_mfma_f32_16x16x32_bf16 v[60:63], v[162:165], v[186:189], v[60:63]
	v_mfma_f32_16x16x32_bf16 v[40:43], v[154:157], v[194:197], v[40:43]
	v_mfma_f32_16x16x32_bf16 v[44:47], v[162:165], v[194:197], v[44:47]
	v_mfma_f32_16x16x32_bf16 v[24:27], v[154:157], v[202:205], v[24:27]
	v_mfma_f32_16x16x32_bf16 v[28:31], v[162:165], v[202:205], v[28:31]
	v_mfma_f32_16x16x32_bf16 v[8:11], v[154:157], v[210:213], v[8:11]
	v_mfma_f32_16x16x32_bf16 v[12:15], v[162:165], v[210:213], v[12:15]
	s_setprio 0
	s_setprio 1
	v_mfma_f32_16x16x32_bf16 v[48:51], v[166:169], v[182:185], v[48:51]
	v_mfma_f32_16x16x32_bf16 v[52:55], v[174:177], v[182:185], v[52:55]
	v_mfma_f32_16x16x32_bf16 v[32:35], v[166:169], v[190:193], v[32:35]
	v_mfma_f32_16x16x32_bf16 v[36:39], v[174:177], v[190:193], v[36:39]
	v_mfma_f32_16x16x32_bf16 v[16:19], v[166:169], v[198:201], v[16:19]
	v_mfma_f32_16x16x32_bf16 v[20:23], v[174:177], v[198:201], v[20:23]
	v_mfma_f32_16x16x32_bf16 v[4:7], v[166:169], v[206:209], v[4:7]
	v_mfma_f32_16x16x32_bf16 v[0:3], v[174:177], v[206:209], v[0:3]
	v_mfma_f32_16x16x32_bf16 v[48:51], v[170:173], v[186:189], v[48:51]
	v_mfma_f32_16x16x32_bf16 v[52:55], v[178:181], v[186:189], v[52:55]
	v_mfma_f32_16x16x32_bf16 v[32:35], v[170:173], v[194:197], v[32:35]
	v_mfma_f32_16x16x32_bf16 v[36:39], v[178:181], v[194:197], v[36:39]
	v_mfma_f32_16x16x32_bf16 v[16:19], v[170:173], v[202:205], v[16:19]
	v_mfma_f32_16x16x32_bf16 v[20:23], v[178:181], v[202:205], v[20:23]
	v_mfma_f32_16x16x32_bf16 v[4:7], v[170:173], v[210:213], v[4:7]
	v_mfma_f32_16x16x32_bf16 v[0:3], v[178:181], v[210:213], v[0:3]
	s_setprio 0
	s_barrier
	s_add_i32 s65, s65, 2
	s_add_u32 s39, s39, 0x100
	s_addc_u32 s64, s64, 0
	s_cmpk_gt_u32 s65, 0x55
	s_mov_b64 s[40:41], s[4:5]
	s_cbranch_scc0 .LBB0_1912
	s_and_b64 vcc, exec, s[14:15]
	s_cbranch_vccz .LBB0_1915
	s_barrier
